# snake order also in the peeled first-iteration phases and the PLE GEMM where verifiable
# baseline (speedup 1.0000x reference)
;     __device__ __forceinline__ bool next(int i, Unit& u) const { if (i >= count) return false; const int L = first + i; u.pm = L / nN; u.pn = L % nN; return true; }
; #define PG8_STAGE(bufoff, gbase, voff) do { if constexpr (ABL & 1) break; glds16s<(bufoff)>((voff)[0], (const void*)(gbase), ldsbw); glds16s<(bufoff) + 8192>((voff)[1], (const void*)(gbase), ldsbw); } while (0)
; #define PG8_LDA(dst, b, h) do { if constexpr (ABL & 4) break; _Pragma("unroll") for (int m = 0; m < 4; ++m) _Pragma("unroll") for (int k = 0; k < 2; ++k) dst[m][k] = *(const LAS f16x8*)(lds + PG8_SA(b, h) + aoff + m * 2048 + k * 1024); } while (0)
; #define PG8_LDB(dst, b, h) do { if constexpr (ABL & 4) break; _Pragma("unroll") for (int n = 0; n < 2; ++n) _Pragma("unroll") for (int k = 0; k < 2; ++k) dst[n][k] = *(const LAS f16x8*)(lds + PG8_SB(b, h) + boff + n * 2048 + k * 1024); } while (0)
; #define PG8_MMAF(ai, bj, At, Bt) do { if (t == 0) PG8_MMA0(ai, bj, At, Bt); else PG8_MMA(ai, bj, At, Bt); } while (0)
; #define PG8_WAIT_V(n) asm volatile("s_waitcnt vmcnt(" #n ")" ::: "memory")
; #define PG8_BAR __builtin_amdgcn_s_barrier()
;     ...
;         const bool has_next = S.next(ui + 1, nxt);
;         const char* nA = has_next ? (const char*)g.A + (size_t)nxt.pm * tstep : cA; const char* nB = has_next ? (const char*)g.Bt + (size_t)nxt.pn * tstep : cB;
;         for (int t = 0; t < nt; t += 2) {
;             const bool last = (t == nt - 2);
;             const char* a1 = cA + (size_t)(t + 1) * kstep;
;             const char* a2 = last ? nA : cA + (size_t)(t + 2) * kstep; const char* b2 = last ? nB : cB + (size_t)(t + 2) * kstep;
;             const char* a3 = a2 + kstep; const char* b3 = b2 + kstep;
;             if (last && has_next) S.a_ready(nxt);
;             if constexpr (SP2) {
;             PG8_LDB(B0, 0, 0); PG8_LDB(B1, 0, 1); PG8_SCHED; PG8_LDA(At, 0, 0); PG8_STAGE(PG8_SA(1, 1), a1 + hstep, voffA);
;             PG8_WAIT_V(8); PG8_WAIT_L(0); PG8_BAR; PG8_MMAF(0, 0, At, B0); PG8_MMAF(0, 1, At, B1); PG8_BAR; PG8_SCHED;
;             const bool fin = last && !has_next;
;             PG8_LDA(At, 0, 1); if (!fin) { PG8_STAGE(PG8_SB(0, 0), b2, voffB); PG8_STAGE(PG8_SB(0, 1), b2 + hstep, voffB); PG8_STAGE(PG8_SA(0, 0), a2, voffA); }
;             if (!fin) PG8_WAIT_V(8); else PG8_WAIT_V(2); PG8_WAIT_L(0); PG8_BAR; PG8_MMAF(1, 0, At, B0); PG8_MMAF(1, 1, At, B1); PG8_BAR; PG8_SCHED;
.LBB0_229:
	s_ashr_i32 s53, s52, 31
	s_lshl_b64 s[8:9], s[52:53], 19
	s_add_u32 s54, s74, s8
	s_addc_u32 s55, s75, s9
	s_and_b64 s[8:9], exec, s[4:5]
	ds_read_b128 v[2:5], v236
	ds_read_b128 v[6:9], v236 offset:1024
	ds_read_b128 v[10:13], v236 offset:2048
	ds_read_b128 v[14:17], v236 offset:3072
	ds_read_b128 v[18:21], v237
	ds_read_b128 v[22:25], v237 offset:1024
	ds_read_b128 v[26:29], v237 offset:2048
	ds_read_b128 v[30:33], v237 offset:3072
	s_cselect_b32 s11, s63, s55
	s_cselect_b32 s35, s62, s54
	s_ashr_i32 s1, s0, 31
	s_lshl_b64 s[8:9], s[0:1], 19
	s_add_u32 s56, s90, s8
	s_addc_u32 s57, s91, s9
	s_and_b64 s[8:9], exec, s[4:5]
	s_cselect_b32 s1, s7, s57
	s_cselect_b32 s46, s6, s56
	s_add_u32 s8, s62, 0x100
	s_addc_u32 s9, s63, 0
	s_add_u32 s64, s6, 0x100
	s_addc_u32 s65, s7, 0
	s_add_u32 s24, s62, 0x180
	s_addc_u32 s25, s63, 0
	ds_read_b128 v[34:37], v238
	ds_read_b128 v[38:41], v238 offset:1024
	ds_read_b128 v[42:45], v238 offset:2048
	ds_read_b128 v[46:49], v238 offset:3072
	ds_read_b128 v[50:53], v238 offset:4096
	ds_read_b128 v[54:57], v238 offset:5120
	ds_read_b128 v[58:61], v238 offset:6144
	ds_read_b128 v[62:65], v238 offset:7168
	s_add_u32 s26, s6, 0x180
	s_addc_u32 s27, s7, 0
	s_add_u32 s76, s62, 0x40080
	s_addc_u32 s77, s63, 0
	s_add_u32 m0, s28, 0xc000
	s_nop 0
	global_load_lds_dwordx4 v232, s[76:77]
	s_nop 0
	s_add_u32 m0, s28, 0xe000
	s_nop 0
	global_load_lds_dwordx4 v234, s[76:77]
	s_waitcnt vmcnt(8)
	s_waitcnt lgkmcnt(0)
	s_barrier
	v_mfma_f32_16x16x32_f16 v[86:89], v[10:13], v[50:53], 0
	s_setprio 1
	v_mfma_f32_16x16x32_f16 v[90:93], v[14:17], v[54:57], v[86:89]
	v_mfma_f32_16x16x32_f16 v[70:73], v[14:17], v[38:41], 0
	v_mfma_f32_16x16x32_f16 v[70:73], v[10:13], v[34:37], v[70:73]
	v_mfma_f32_16x16x32_f16 v[66:69], v[2:5], v[34:37], 0
	v_mfma_f32_16x16x32_f16 v[66:69], v[6:9], v[38:41], v[66:69]
	v_mfma_f32_16x16x32_f16 v[86:89], v[6:9], v[62:65], 0
	v_mfma_f32_16x16x32_f16 v[94:97], v[2:5], v[58:61], v[86:89]
	v_mfma_f32_16x16x32_f16 v[74:77], v[2:5], v[42:45], 0
	v_mfma_f32_16x16x32_f16 v[74:77], v[6:9], v[46:49], v[74:77]
	v_mfma_f32_16x16x32_f16 v[78:81], v[14:17], v[46:49], 0
	v_mfma_f32_16x16x32_f16 v[78:81], v[10:13], v[42:45], v[78:81]
	v_mfma_f32_16x16x32_f16 v[86:89], v[10:13], v[58:61], 0
	v_mfma_f32_16x16x32_f16 v[106:109], v[14:17], v[62:65], v[86:89]
	v_mfma_f32_16x16x32_f16 v[82:85], v[2:5], v[50:53], 0
	v_mfma_f32_16x16x32_f16 v[82:85], v[6:9], v[54:57], v[82:85]
	v_mfma_f32_16x16x32_f16 v[86:89], v[18:21], v[34:37], 0
	v_mfma_f32_16x16x32_f16 v[34:37], v[26:29], v[34:37], 0
	v_mfma_f32_16x16x32_f16 v[110:113], v[22:25], v[38:41], v[86:89]
	v_mfma_f32_16x16x32_f16 v[34:37], v[30:33], v[38:41], v[34:37]
	v_mfma_f32_16x16x32_f16 v[38:41], v[18:21], v[42:45], 0
	v_mfma_f32_16x16x32_f16 v[42:45], v[26:29], v[42:45], 0
	v_mfma_f32_16x16x32_f16 v[38:41], v[22:25], v[46:49], v[38:41]
	v_mfma_f32_16x16x32_f16 v[42:45], v[30:33], v[46:49], v[42:45]
	v_mfma_f32_16x16x32_f16 v[46:49], v[18:21], v[50:53], 0
	v_mfma_f32_16x16x32_f16 v[50:53], v[26:29], v[50:53], 0
	v_mfma_f32_16x16x32_f16 v[46:49], v[22:25], v[54:57], v[46:49]
	v_mfma_f32_16x16x32_f16 v[54:57], v[30:33], v[54:57], v[50:53]
	v_mfma_f32_16x16x32_f16 v[50:53], v[18:21], v[58:61], 0
	v_mfma_f32_16x16x32_f16 v[130:133], v[22:25], v[62:65], v[50:53]
	v_mfma_f32_16x16x32_f16 v[50:53], v[26:29], v[58:61], 0
	v_mfma_f32_16x16x32_f16 v[62:65], v[30:33], v[62:65], v[50:53]
	s_barrier
	s_setprio 0
	s_nop 4
	ds_read_b128 v[50:53], v238 offset:16384
	ds_read_b128 v[58:61], v238 offset:17408
	ds_read_b128 v[86:89], v238 offset:18432
	ds_read_b128 v[98:101], v238 offset:19456
	ds_read_b128 v[102:105], v238 offset:20480
	ds_read_b128 v[114:117], v238 offset:21504
	ds_read_b128 v[118:121], v238 offset:22528
	ds_read_b128 v[122:125], v238 offset:23552
	s_add_u32 m0, s28, 0x10000
	s_nop 0
	global_load_lds_dwordx4 v233, s[64:65]
	s_nop 0
	s_add_u32 m0, s28, 0x12000
	s_nop 0
	global_load_lds_dwordx4 v235, s[64:65]
	s_add_u32 s64, s6, 0x40100
	s_addc_u32 s65, s7, 0
	s_add_u32 m0, s28, 0x14000
	s_nop 0
	global_load_lds_dwordx4 v233, s[64:65]
	s_nop 0
	s_add_u32 m0, s28, 0x16000
	s_nop 0
	global_load_lds_dwordx4 v235, s[64:65]
	s_nop 0
	s_add_u32 m0, s28, 0
	s_nop 0
	global_load_lds_dwordx4 v232, s[8:9]
	s_nop 0
	s_add_u32 m0, s28, 0x2000
	s_nop 0
	global_load_lds_dwordx4 v234, s[8:9]
	s_waitcnt vmcnt(8)
	s_waitcnt lgkmcnt(0)
	s_barrier
	v_mfma_f32_16x16x32_f16 v[126:129], v[2:5], v[50:53], 0
	s_setprio 1
	v_mfma_f32_16x16x32_f16 v[134:137], v[6:9], v[58:61], v[126:129]
	v_mfma_f32_16x16x32_f16 v[126:129], v[10:13], v[50:53], 0
	v_mfma_f32_16x16x32_f16 v[138:141], v[14:17], v[58:61], v[126:129]
	v_mfma_f32_16x16x32_f16 v[126:129], v[2:5], v[86:89], 0
	v_mfma_f32_16x16x32_f16 v[142:145], v[6:9], v[98:101], v[126:129]
	v_mfma_f32_16x16x32_f16 v[126:129], v[10:13], v[86:89], 0
	v_mfma_f32_16x16x32_f16 v[146:149], v[14:17], v[98:101], v[126:129]
	v_mfma_f32_16x16x32_f16 v[126:129], v[2:5], v[102:105], 0
	v_mfma_f32_16x16x32_f16 v[150:153], v[6:9], v[114:117], v[126:129]
	v_mfma_f32_16x16x32_f16 v[2:5], v[2:5], v[118:121], 0
	v_mfma_f32_16x16x32_f16 v[2:5], v[6:9], v[122:125], v[2:5]
	v_mfma_f32_16x16x32_f16 v[6:9], v[10:13], v[118:121], 0
	v_mfma_f32_16x16x32_f16 v[126:129], v[10:13], v[102:105], 0
	v_mfma_f32_16x16x32_f16 v[154:157], v[14:17], v[114:117], v[126:129]
	v_mfma_f32_16x16x32_f16 v[10:13], v[14:17], v[122:125], v[6:9]
	v_mfma_f32_16x16x32_f16 v[6:9], v[18:21], v[50:53], 0
	v_mfma_f32_16x16x32_f16 v[158:161], v[22:25], v[58:61], v[6:9]
	v_mfma_f32_16x16x32_f16 v[6:9], v[26:29], v[50:53], 0
	v_mfma_f32_16x16x32_f16 v[162:165], v[30:33], v[58:61], v[6:9]
	v_mfma_f32_16x16x32_f16 v[6:9], v[18:21], v[86:89], 0
	v_mfma_f32_16x16x32_f16 v[166:169], v[22:25], v[98:101], v[6:9]
	v_mfma_f32_16x16x32_f16 v[6:9], v[26:29], v[86:89], 0
	v_mfma_f32_16x16x32_f16 v[170:173], v[30:33], v[98:101], v[6:9]
	v_mfma_f32_16x16x32_f16 v[6:9], v[18:21], v[102:105], 0
	v_mfma_f32_16x16x32_f16 v[174:177], v[22:25], v[114:117], v[6:9]
	v_mfma_f32_16x16x32_f16 v[6:9], v[26:29], v[102:105], 0
	v_mfma_f32_16x16x32_f16 v[178:181], v[30:33], v[114:117], v[6:9]
	v_mfma_f32_16x16x32_f16 v[6:9], v[18:21], v[118:121], 0
	v_mfma_f32_16x16x32_f16 v[22:25], v[22:25], v[122:125], v[6:9]
	v_mfma_f32_16x16x32_f16 v[6:9], v[26:29], v[118:121], 0
	v_mfma_f32_16x16x32_f16 v[182:185], v[30:33], v[122:125], v[6:9]
	s_barrier
; #define PG8_STAGE(bufoff, gbase, voff) do { if constexpr (ABL & 1) break; glds16s<(bufoff)>((voff)[0], (const void*)(gbase), ldsbw); glds16s<(bufoff) + 8192>((voff)[1], (const void*)(gbase), ldsbw); } while (0)
; #define PG8_LDA(dst, b, h) do { if constexpr (ABL & 4) break; _Pragma("unroll") for (int m = 0; m < 4; ++m) _Pragma("unroll") for (int k = 0; k < 2; ++k) dst[m][k] = *(const LAS f16x8*)(lds + PG8_SA(b, h) + aoff + m * 2048 + k * 1024); } while (0)
; #define PG8_LDB(dst, b, h) do { if constexpr (ABL & 4) break; _Pragma("unroll") for (int n = 0; n < 2; ++n) _Pragma("unroll") for (int k = 0; k < 2; ++k) dst[n][k] = *(const LAS f16x8*)(lds + PG8_SB(b, h) + boff + n * 2048 + k * 1024); } while (0)
; #define PG8_MMA(ai, bj, At, Bt) do { if constexpr (ABL & 2) break; __builtin_amdgcn_s_setprio(1); _Pragma("unroll") for (int m = 0; m < 4; ++m) _Pragma("unroll") for (int n = 0; n < 2; ++n) _Pragma("unroll") for (int k = 0; k < 2; ++k) \
;         acc[ai][bj][m][n] = __builtin_amdgcn_mfma_f32_16x16x32_f16(Bt[n][k], At[m][k], acc[ai][bj][m][n], 0, 0, 0); __builtin_amdgcn_s_setprio(0); } while (0)
; #define PG8_WAIT_V(n) asm volatile("s_waitcnt vmcnt(" #n ")" ::: "memory")
; #define PG8_WAIT_L(n) asm volatile("s_waitcnt lgkmcnt(" #n ")" ::: "memory")
; #define PG8_BAR __builtin_amdgcn_s_barrier()
; #define PG8_SCHED __builtin_amdgcn_sched_barrier(0)
;     ...
;             PG8_LDB(B0, 1, 0); PG8_LDB(B1, 1, 1); PG8_SCHED; PG8_LDA(At, 1, 0); if (!fin) PG8_STAGE(PG8_SA(0, 1), a2 + hstep, voffA);
;             if (!fin) PG8_WAIT_V(8); else PG8_WAIT_V(0); PG8_WAIT_L(0); PG8_BAR; PG8_MMA(0, 0, At, B0); PG8_MMA(0, 1, At, B1); PG8_BAR; PG8_SCHED;
;             PG8_LDA(At, 1, 1); if (!fin) { PG8_STAGE(PG8_SB(1, 0), b3, voffB); PG8_STAGE(PG8_SB(1, 1), b3 + hstep, voffB); PG8_STAGE(PG8_SA(1, 0), a3, voffA); }
;             if (!fin) PG8_WAIT_V(8); PG8_WAIT_L(0); PG8_BAR; PG8_MMA(1, 0, At, B0); PG8_MMA(1, 1, At, B1); PG8_BAR; PG8_SCHED;
	s_setprio 0
	s_nop 4
	ds_read_b128 v[6:9], v239
	ds_read_b128 v[26:29], v239 offset:1024
	ds_read_b128 v[186:189], v239 offset:2048
	ds_read_b128 v[190:193], v239 offset:3072
	ds_read_b128 v[206:209], v240
	ds_read_b128 v[210:213], v240 offset:1024
	ds_read_b128 v[214:217], v240 offset:2048
	ds_read_b128 v[218:221], v240 offset:3072
	ds_read_b128 v[14:17], v238 offset:32768
	ds_read_b128 v[18:21], v238 offset:33792
	ds_read_b128 v[30:33], v238 offset:34816
	ds_read_b128 v[222:225], v238 offset:35840
	ds_read_b128 v[226:229], v238 offset:36864
	ds_read_b128 v[242:245], v238 offset:37888
	ds_read_b128 v[246:249], v238 offset:38912
	ds_read_b128 v[250:253], v238 offset:39936
	s_add_u32 s62, s62, 0x40100
	s_addc_u32 s63, s63, 0
	s_add_u32 m0, s28, 0x4000
	s_nop 0
	global_load_lds_dwordx4 v232, s[62:63]
	s_nop 0
	s_add_u32 m0, s28, 0x6000
	s_nop 0
	global_load_lds_dwordx4 v234, s[62:63]
	s_waitcnt vmcnt(8)
	s_waitcnt lgkmcnt(0)
	s_barrier
	v_mfma_f32_16x16x32_f16 v[50:53], v[6:9], v[14:17], v[66:69]
	s_setprio 1
	v_mfma_f32_16x16x32_f16 v[118:121], v[26:29], v[18:21], v[50:53]
	v_mfma_f32_16x16x32_f16 v[50:53], v[186:189], v[14:17], v[70:73]
	v_mfma_f32_16x16x32_f16 v[114:117], v[190:193], v[18:21], v[50:53]
	v_mfma_f32_16x16x32_f16 v[50:53], v[6:9], v[30:33], v[74:77]
	v_mfma_f32_16x16x32_f16 v[102:105], v[26:29], v[222:225], v[50:53]
	v_mfma_f32_16x16x32_f16 v[50:53], v[186:189], v[30:33], v[78:81]
	v_mfma_f32_16x16x32_f16 v[98:101], v[190:193], v[222:225], v[50:53]
	v_mfma_f32_16x16x32_f16 v[50:53], v[6:9], v[226:229], v[82:85]
	v_mfma_f32_16x16x32_f16 v[86:89], v[26:29], v[242:245], v[50:53]
	v_mfma_f32_16x16x32_f16 v[50:53], v[186:189], v[226:229], v[90:93]
	v_mfma_f32_16x16x32_f16 v[78:81], v[190:193], v[242:245], v[50:53]
	v_mfma_f32_16x16x32_f16 v[50:53], v[6:9], v[246:249], v[94:97]
	v_mfma_f32_16x16x32_f16 v[58:61], v[26:29], v[250:253], v[50:53]
	v_mfma_f32_16x16x32_f16 v[50:53], v[186:189], v[246:249], v[106:109]
	v_mfma_f32_16x16x32_f16 v[50:53], v[190:193], v[250:253], v[50:53]
	v_mfma_f32_16x16x32_f16 v[66:69], v[206:209], v[14:17], v[110:113]
	v_mfma_f32_16x16x32_f16 v[126:129], v[210:213], v[18:21], v[66:69]
	v_mfma_f32_16x16x32_f16 v[14:17], v[214:217], v[14:17], v[34:37]
	v_mfma_f32_16x16x32_f16 v[122:125], v[218:221], v[18:21], v[14:17]
	v_mfma_f32_16x16x32_f16 v[14:17], v[206:209], v[30:33], v[38:41]
	v_mfma_f32_16x16x32_f16 v[110:113], v[210:213], v[222:225], v[14:17]
	v_mfma_f32_16x16x32_f16 v[14:17], v[214:217], v[30:33], v[42:45]
	v_mfma_f32_16x16x32_f16 v[106:109], v[218:221], v[222:225], v[14:17]
	v_mfma_f32_16x16x32_f16 v[14:17], v[206:209], v[226:229], v[46:49]
	v_mfma_f32_16x16x32_f16 v[94:97], v[210:213], v[242:245], v[14:17]
	v_mfma_f32_16x16x32_f16 v[14:17], v[214:217], v[226:229], v[54:57]
	v_mfma_f32_16x16x32_f16 v[90:93], v[218:221], v[242:245], v[14:17]
	v_mfma_f32_16x16x32_f16 v[14:17], v[206:209], v[246:249], v[130:133]
	v_mfma_f32_16x16x32_f16 v[74:77], v[210:213], v[250:253], v[14:17]
	v_mfma_f32_16x16x32_f16 v[14:17], v[214:217], v[246:249], v[62:65]
	v_mfma_f32_16x16x32_f16 v[66:69], v[218:221], v[250:253], v[14:17]
	s_barrier
	s_setprio 0
	ds_read_b128 v[38:41], v238 offset:49152
	ds_read_b128 v[42:45], v238 offset:50176
	ds_read_b128 v[130:133], v238 offset:51200
	ds_read_b128 v[222:225], v238 offset:52224
	ds_read_b128 v[226:229], v238 offset:53248
	ds_read_b128 v[242:245], v238 offset:54272
	ds_read_b128 v[246:249], v238 offset:55296
	ds_read_b128 v[250:253], v238 offset:56320
	s_add_u32 m0, s28, 0x18000
	s_nop 0
	global_load_lds_dwordx4 v233, s[26:27]
	s_nop 0
	s_add_u32 m0, s28, 0x1a000
	s_nop 0
	global_load_lds_dwordx4 v235, s[26:27]
	s_add_u32 s26, s6, 0x40180
	s_addc_u32 s27, s7, 0
	s_add_u32 m0, s28, 0x1c000
	s_nop 0
	global_load_lds_dwordx4 v233, s[26:27]
	s_nop 0
	s_add_u32 m0, s28, 0x1e000
	s_nop 0
	global_load_lds_dwordx4 v235, s[26:27]
	s_nop 0
	s_add_u32 m0, s28, 0x8000
	s_nop 0
	global_load_lds_dwordx4 v232, s[24:25]
	s_nop 0
	s_add_u32 m0, s28, 0xa000
	s_nop 0
	global_load_lds_dwordx4 v234, s[24:25]
	s_waitcnt vmcnt(8)
	s_waitcnt lgkmcnt(0)
	s_barrier
	v_mfma_f32_16x16x32_f16 v[14:17], v[6:9], v[38:41], v[134:137]
	s_setprio 1
	v_mfma_f32_16x16x32_f16 v[54:57], v[26:29], v[42:45], v[14:17]
	v_mfma_f32_16x16x32_f16 v[14:17], v[190:193], v[42:45], v[138:141]
	v_mfma_f32_16x16x32_f16 v[46:49], v[186:189], v[38:41], v[14:17]
	v_mfma_f32_16x16x32_f16 v[14:17], v[6:9], v[130:133], v[142:145]
	v_mfma_f32_16x16x32_f16 v[34:37], v[26:29], v[222:225], v[14:17]
	v_mfma_f32_16x16x32_f16 v[14:17], v[190:193], v[222:225], v[146:149]
	v_mfma_f32_16x16x32_f16 v[30:33], v[186:189], v[130:133], v[14:17]
	v_mfma_f32_16x16x32_f16 v[14:17], v[6:9], v[226:229], v[150:153]
	v_mfma_f32_16x16x32_f16 v[18:21], v[26:29], v[242:245], v[14:17]
	v_mfma_f32_16x16x32_f16 v[14:17], v[190:193], v[242:245], v[154:157]
	v_mfma_f32_16x16x32_f16 v[14:17], v[186:189], v[226:229], v[14:17]
	v_mfma_f32_16x16x32_f16 v[2:5], v[6:9], v[246:249], v[2:5]
	v_mfma_f32_16x16x32_f16 v[6:9], v[26:29], v[250:253], v[2:5]
	v_mfma_f32_16x16x32_f16 v[2:5], v[190:193], v[250:253], v[10:13]
	v_mfma_f32_16x16x32_f16 v[2:5], v[186:189], v[246:249], v[2:5]
	v_mfma_f32_16x16x32_f16 v[10:13], v[206:209], v[38:41], v[158:161]
	v_mfma_f32_16x16x32_f16 v[82:85], v[210:213], v[42:45], v[10:13]
	v_mfma_f32_16x16x32_f16 v[10:13], v[218:221], v[42:45], v[162:165]
	v_mfma_f32_16x16x32_f16 v[70:73], v[214:217], v[38:41], v[10:13]
	v_mfma_f32_16x16x32_f16 v[10:13], v[206:209], v[130:133], v[166:169]
	v_mfma_f32_16x16x32_f16 v[62:65], v[210:213], v[222:225], v[10:13]
	v_mfma_f32_16x16x32_f16 v[10:13], v[218:221], v[222:225], v[170:173]
	v_mfma_f32_16x16x32_f16 v[42:45], v[214:217], v[130:133], v[10:13]
	v_mfma_f32_16x16x32_f16 v[10:13], v[206:209], v[226:229], v[174:177]
	v_mfma_f32_16x16x32_f16 v[38:41], v[210:213], v[242:245], v[10:13]
	v_mfma_f32_16x16x32_f16 v[10:13], v[218:221], v[242:245], v[178:181]
	v_mfma_f32_16x16x32_f16 v[26:29], v[214:217], v[226:229], v[10:13]
	v_mfma_f32_16x16x32_f16 v[10:13], v[206:209], v[246:249], v[22:25]
	v_mfma_f32_16x16x32_f16 v[22:25], v[210:213], v[250:253], v[10:13]
	v_mfma_f32_16x16x32_f16 v[10:13], v[218:221], v[250:253], v[182:185]
	v_mfma_f32_16x16x32_f16 v[10:13], v[214:217], v[246:249], v[10:13]
	s_barrier
	s_setprio 0
	s_add_u32 s53, s6, 0x200
	s_addc_u32 s61, s7, 0
	s_mov_b32 s64, 0
	s_branch .LBB0_231

;     __device__ __forceinline__ bool next(int i, Unit& u) const { if (i >= count) return false; const int L = first + i; u.pm = L / nN; u.pn = L % nN; return true; }
; #define PG8_STAGE(bufoff, gbase, voff) do { if constexpr (ABL & 1) break; glds16s<(bufoff)>((voff)[0], (const void*)(gbase), ldsbw); glds16s<(bufoff) + 8192>((voff)[1], (const void*)(gbase), ldsbw); } while (0)
; #define PG8_LDA(dst, b, h) do { if constexpr (ABL & 4) break; _Pragma("unroll") for (int m = 0; m < 4; ++m) _Pragma("unroll") for (int k = 0; k < 2; ++k) dst[m][k] = *(const LAS f16x8*)(lds + PG8_SA(b, h) + aoff + m * 2048 + k * 1024); } while (0)
; #define PG8_LDB(dst, b, h) do { if constexpr (ABL & 4) break; _Pragma("unroll") for (int n = 0; n < 2; ++n) _Pragma("unroll") for (int k = 0; k < 2; ++k) dst[n][k] = *(const LAS f16x8*)(lds + PG8_SB(b, h) + boff + n * 2048 + k * 1024); } while (0)
; #define PG8_MMAF(ai, bj, At, Bt) do { if (t == 0) PG8_MMA0(ai, bj, At, Bt); else PG8_MMA(ai, bj, At, Bt); } while (0)
; #define PG8_WAIT_V(n) asm volatile("s_waitcnt vmcnt(" #n ")" ::: "memory")
; #define PG8_BAR __builtin_amdgcn_s_barrier()
;     ...
;         const bool has_next = S.next(ui + 1, nxt);
;         const char* nA = has_next ? (const char*)g.A + (size_t)nxt.pm * tstep : cA; const char* nB = has_next ? (const char*)g.Bt + (size_t)nxt.pn * tstep : cB;
;         for (int t = 0; t < nt; t += 2) {
;             const bool last = (t == nt - 2);
;             const char* a1 = cA + (size_t)(t + 1) * kstep;
;             const char* a2 = last ? nA : cA + (size_t)(t + 2) * kstep; const char* b2 = last ? nB : cB + (size_t)(t + 2) * kstep;
;             const char* a3 = a2 + kstep; const char* b3 = b2 + kstep;
;             if (last && has_next) S.a_ready(nxt);
;             if constexpr (SP2) {
;             PG8_LDB(B0, 0, 0); PG8_LDB(B1, 0, 1); PG8_SCHED; PG8_LDA(At, 0, 0); PG8_STAGE(PG8_SA(1, 1), a1 + hstep, voffA);
;             PG8_WAIT_V(8); PG8_WAIT_L(0); PG8_BAR; PG8_MMAF(0, 0, At, B0); PG8_MMAF(0, 1, At, B1); PG8_BAR; PG8_SCHED;
;             const bool fin = last && !has_next;
;             PG8_LDA(At, 0, 1); if (!fin) { PG8_STAGE(PG8_SB(0, 0), b2, voffB); PG8_STAGE(PG8_SB(0, 1), b2 + hstep, voffB); PG8_STAGE(PG8_SA(0, 0), a2, voffA); }
;             if (!fin) PG8_WAIT_V(8); else PG8_WAIT_V(2); PG8_WAIT_L(0); PG8_BAR; PG8_MMAF(1, 0, At, B0); PG8_MMAF(1, 1, At, B1); PG8_BAR; PG8_SCHED;
.LBB0_748:
	s_ashr_i32 s47, s46, 31
	s_lshl_b64 s[8:9], s[46:47], 19
	s_add_u32 s48, s12, s8
	s_addc_u32 s49, s13, s9
	s_and_b64 s[8:9], exec, s[4:5]
	s_waitcnt lgkmcnt(0)
	ds_read_b128 v[2:5], v222
	ds_read_b128 v[6:9], v222 offset:1024
	ds_read_b128 v[10:13], v222 offset:2048
	ds_read_b128 v[14:17], v222 offset:3072
	ds_read_b128 v[18:21], v223
	ds_read_b128 v[22:25], v223 offset:1024
	ds_read_b128 v[26:29], v223 offset:2048
	ds_read_b128 v[30:33], v223 offset:3072
	s_cselect_b32 s47, s31, s49
	s_cselect_b32 s55, s30, s48
	s_ashr_i32 s45, s44, 31
	s_lshl_b64 s[8:9], s[44:45], 19
	s_add_u32 s50, s90, s8
	s_addc_u32 s51, s91, s9
	s_and_b64 s[8:9], exec, s[4:5]
	s_cselect_b32 s45, s7, s51
	s_cselect_b32 s58, s6, s50
	s_add_u32 s56, s30, 0x100
	s_addc_u32 s57, s31, 0
	s_add_u32 s26, s6, 0x100
	s_addc_u32 s27, s7, 0
	s_add_u32 s8, s30, 0x180
	s_addc_u32 s9, s31, 0
	ds_read_b128 v[34:37], v224
	ds_read_b128 v[38:41], v224 offset:1024
	ds_read_b128 v[42:45], v224 offset:2048
	ds_read_b128 v[46:49], v224 offset:3072
	ds_read_b128 v[50:53], v224 offset:4096
	ds_read_b128 v[54:57], v224 offset:5120
	ds_read_b128 v[58:61], v224 offset:6144
	ds_read_b128 v[62:65], v224 offset:7168
	s_add_u32 s24, s6, 0x180
	s_addc_u32 s25, s7, 0
	s_add_u32 s60, s30, 0x40080
	s_addc_u32 s61, s31, 0
	s_add_u32 m0, s14, 0xc000
	s_nop 0
	global_load_lds_dwordx4 v1, s[60:61]
	s_nop 0
	s_add_u32 m0, s14, 0xe000
	s_nop 0
	global_load_lds_dwordx4 v213, s[60:61]
	s_waitcnt vmcnt(8)
	s_waitcnt lgkmcnt(0)
	s_barrier
	v_mfma_f32_16x16x32_f16 v[66:69], v[2:5], v[34:37], 0
	s_setprio 1
	v_mfma_f32_16x16x32_f16 v[66:69], v[6:9], v[38:41], v[66:69]
	v_mfma_f32_16x16x32_f16 v[70:73], v[14:17], v[38:41], 0
	v_mfma_f32_16x16x32_f16 v[70:73], v[10:13], v[34:37], v[70:73]
	v_mfma_f32_16x16x32_f16 v[78:81], v[10:13], v[42:45], 0
	v_mfma_f32_16x16x32_f16 v[78:81], v[14:17], v[46:49], v[78:81]
	v_mfma_f32_16x16x32_f16 v[94:97], v[14:17], v[62:65], 0
	v_mfma_f32_16x16x32_f16 v[94:97], v[10:13], v[58:61], v[94:97]
	v_mfma_f32_16x16x32_f16 v[90:93], v[2:5], v[58:61], 0
	v_mfma_f32_16x16x32_f16 v[90:93], v[6:9], v[62:65], v[90:93]
	v_mfma_f32_16x16x32_f16 v[82:85], v[6:9], v[54:57], 0
	v_mfma_f32_16x16x32_f16 v[82:85], v[2:5], v[50:53], v[82:85]
	v_mfma_f32_16x16x32_f16 v[74:77], v[2:5], v[42:45], 0
	v_mfma_f32_16x16x32_f16 v[74:77], v[6:9], v[46:49], v[74:77]
	v_mfma_f32_16x16x32_f16 v[86:89], v[10:13], v[50:53], 0
	v_mfma_f32_16x16x32_f16 v[86:89], v[14:17], v[54:57], v[86:89]
	v_mfma_f32_16x16x32_f16 v[98:101], v[18:21], v[34:37], 0
	v_mfma_f32_16x16x32_f16 v[98:101], v[22:25], v[38:41], v[98:101]
	v_mfma_f32_16x16x32_f16 v[34:37], v[26:29], v[34:37], 0
	v_mfma_f32_16x16x32_f16 v[34:37], v[30:33], v[38:41], v[34:37]
	v_mfma_f32_16x16x32_f16 v[38:41], v[18:21], v[42:45], 0
	v_mfma_f32_16x16x32_f16 v[38:41], v[22:25], v[46:49], v[38:41]
	v_mfma_f32_16x16x32_f16 v[42:45], v[26:29], v[42:45], 0
	v_mfma_f32_16x16x32_f16 v[42:45], v[30:33], v[46:49], v[42:45]
	v_mfma_f32_16x16x32_f16 v[46:49], v[18:21], v[50:53], 0
	v_mfma_f32_16x16x32_f16 v[46:49], v[22:25], v[54:57], v[46:49]
	v_mfma_f32_16x16x32_f16 v[50:53], v[26:29], v[50:53], 0
	v_mfma_f32_16x16x32_f16 v[50:53], v[30:33], v[54:57], v[50:53]
	v_mfma_f32_16x16x32_f16 v[54:57], v[18:21], v[58:61], 0
	v_mfma_f32_16x16x32_f16 v[54:57], v[22:25], v[62:65], v[54:57]
	v_mfma_f32_16x16x32_f16 v[58:61], v[26:29], v[58:61], 0
	v_mfma_f32_16x16x32_f16 v[58:61], v[30:33], v[62:65], v[58:61]
	s_barrier
	s_setprio 0
	ds_read_b128 v[62:65], v224 offset:16384
	ds_read_b128 v[102:105], v224 offset:17408
	ds_read_b128 v[106:109], v224 offset:18432
	ds_read_b128 v[110:113], v224 offset:19456
	ds_read_b128 v[114:117], v224 offset:20480
	ds_read_b128 v[118:121], v224 offset:21504
	ds_read_b128 v[122:125], v224 offset:22528
	ds_read_b128 v[126:129], v224 offset:23552
	s_add_u32 m0, s14, 0x10000
	s_nop 0
	global_load_lds_dwordx4 v209, s[26:27]
	s_nop 0
	s_add_u32 m0, s14, 0x12000
	s_nop 0
	global_load_lds_dwordx4 v219, s[26:27]
	s_add_u32 s26, s6, 0x40100
	s_addc_u32 s27, s7, 0
	s_add_u32 m0, s14, 0x14000
	s_nop 0
	global_load_lds_dwordx4 v209, s[26:27]
	s_nop 0
	s_add_u32 m0, s14, 0x16000
	s_nop 0
	global_load_lds_dwordx4 v219, s[26:27]
	s_nop 0
	s_add_u32 m0, s14, 0
	s_nop 0
	global_load_lds_dwordx4 v1, s[56:57]
	s_nop 0
	s_add_u32 m0, s14, 0x2000
	s_nop 0
	global_load_lds_dwordx4 v213, s[56:57]
	s_waitcnt vmcnt(8)
	s_waitcnt lgkmcnt(0)
	s_barrier
	v_mfma_f32_16x16x32_f16 v[130:133], v[2:5], v[62:65], 0
	s_setprio 1
	v_mfma_f32_16x16x32_f16 v[134:137], v[6:9], v[102:105], v[130:133]
	v_mfma_f32_16x16x32_f16 v[130:133], v[10:13], v[62:65], 0
	v_mfma_f32_16x16x32_f16 v[146:149], v[14:17], v[102:105], v[130:133]
	v_mfma_f32_16x16x32_f16 v[130:133], v[2:5], v[106:109], 0
	v_mfma_f32_16x16x32_f16 v[158:161], v[6:9], v[110:113], v[130:133]
	v_mfma_f32_16x16x32_f16 v[130:133], v[10:13], v[106:109], 0
	v_mfma_f32_16x16x32_f16 v[162:165], v[14:17], v[110:113], v[130:133]
	v_mfma_f32_16x16x32_f16 v[130:133], v[2:5], v[114:117], 0
	v_mfma_f32_16x16x32_f16 v[166:169], v[6:9], v[118:121], v[130:133]
	v_mfma_f32_16x16x32_f16 v[2:5], v[2:5], v[122:125], 0
	v_mfma_f32_16x16x32_f16 v[2:5], v[6:9], v[126:129], v[2:5]
	v_mfma_f32_16x16x32_f16 v[6:9], v[10:13], v[122:125], 0
	v_mfma_f32_16x16x32_f16 v[6:9], v[14:17], v[126:129], v[6:9]
	v_mfma_f32_16x16x32_f16 v[130:133], v[10:13], v[114:117], 0
	v_mfma_f32_16x16x32_f16 v[170:173], v[14:17], v[118:121], v[130:133]
	v_mfma_f32_16x16x32_f16 v[10:13], v[18:21], v[62:65], 0
	v_mfma_f32_16x16x32_f16 v[174:177], v[22:25], v[102:105], v[10:13]
	v_mfma_f32_16x16x32_f16 v[10:13], v[26:29], v[62:65], 0
	v_mfma_f32_16x16x32_f16 v[178:181], v[30:33], v[102:105], v[10:13]
	v_mfma_f32_16x16x32_f16 v[10:13], v[18:21], v[106:109], 0
	v_mfma_f32_16x16x32_f16 v[182:185], v[22:25], v[110:113], v[10:13]
	v_mfma_f32_16x16x32_f16 v[10:13], v[26:29], v[106:109], 0
	v_mfma_f32_16x16x32_f16 v[110:113], v[30:33], v[110:113], v[10:13]
	v_mfma_f32_16x16x32_f16 v[10:13], v[18:21], v[114:117], 0
	v_mfma_f32_16x16x32_f16 v[186:189], v[22:25], v[118:121], v[10:13]
	v_mfma_f32_16x16x32_f16 v[10:13], v[26:29], v[114:117], 0
	v_mfma_f32_16x16x32_f16 v[190:193], v[30:33], v[118:121], v[10:13]
	v_mfma_f32_16x16x32_f16 v[10:13], v[18:21], v[122:125], 0
	v_mfma_f32_16x16x32_f16 v[194:197], v[22:25], v[126:129], v[10:13]
	v_mfma_f32_16x16x32_f16 v[10:13], v[26:29], v[122:125], 0
	v_mfma_f32_16x16x32_f16 v[122:125], v[30:33], v[126:129], v[10:13]
	s_barrier
; #define PG8_STAGE(bufoff, gbase, voff) do { if constexpr (ABL & 1) break; glds16s<(bufoff)>((voff)[0], (const void*)(gbase), ldsbw); glds16s<(bufoff) + 8192>((voff)[1], (const void*)(gbase), ldsbw); } while (0)
; #define PG8_LDA(dst, b, h) do { if constexpr (ABL & 4) break; _Pragma("unroll") for (int m = 0; m < 4; ++m) _Pragma("unroll") for (int k = 0; k < 2; ++k) dst[m][k] = *(const LAS f16x8*)(lds + PG8_SA(b, h) + aoff + m * 2048 + k * 1024); } while (0)
; #define PG8_LDB(dst, b, h) do { if constexpr (ABL & 4) break; _Pragma("unroll") for (int n = 0; n < 2; ++n) _Pragma("unroll") for (int k = 0; k < 2; ++k) dst[n][k] = *(const LAS f16x8*)(lds + PG8_SB(b, h) + boff + n * 2048 + k * 1024); } while (0)
; #define PG8_MMA(ai, bj, At, Bt) do { if constexpr (ABL & 2) break; __builtin_amdgcn_s_setprio(1); _Pragma("unroll") for (int m = 0; m < 4; ++m) _Pragma("unroll") for (int n = 0; n < 2; ++n) _Pragma("unroll") for (int k = 0; k < 2; ++k) \
;         acc[ai][bj][m][n] = __builtin_amdgcn_mfma_f32_16x16x32_f16(Bt[n][k], At[m][k], acc[ai][bj][m][n], 0, 0, 0); __builtin_amdgcn_s_setprio(0); } while (0)
; #define PG8_WAIT_V(n) asm volatile("s_waitcnt vmcnt(" #n ")" ::: "memory")
; #define PG8_WAIT_L(n) asm volatile("s_waitcnt lgkmcnt(" #n ")" ::: "memory")
; #define PG8_BAR __builtin_amdgcn_s_barrier()
; #define PG8_SCHED __builtin_amdgcn_sched_barrier(0)
;     ...
;             PG8_LDB(B0, 1, 0); PG8_LDB(B1, 1, 1); PG8_SCHED; PG8_LDA(At, 1, 0); if (!fin) PG8_STAGE(PG8_SA(0, 1), a2 + hstep, voffA);
;             if (!fin) PG8_WAIT_V(8); else PG8_WAIT_V(0); PG8_WAIT_L(0); PG8_BAR; PG8_MMA(0, 0, At, B0); PG8_MMA(0, 1, At, B1); PG8_BAR; PG8_SCHED;
;             PG8_LDA(At, 1, 1); if (!fin) { PG8_STAGE(PG8_SB(1, 0), b3, voffB); PG8_STAGE(PG8_SB(1, 1), b3 + hstep, voffB); PG8_STAGE(PG8_SA(1, 0), a3, voffA); }
;             if (!fin) PG8_WAIT_V(8); PG8_WAIT_L(0); PG8_BAR; PG8_MMA(1, 0, At, B0); PG8_MMA(1, 1, At, B1); PG8_BAR; PG8_SCHED;
	s_setprio 0
	s_nop 4
	ds_read_b128 v[10:13], v225
	ds_read_b128 v[14:17], v225 offset:1024
	ds_read_b128 v[18:21], v225 offset:2048
	ds_read_b128 v[22:25], v225 offset:3072
	ds_read_b128 v[198:201], v226
	ds_read_b128 v[214:217], v226 offset:1024
	ds_read_b128 v[228:231], v226 offset:2048
	ds_read_b128 v[232:235], v226 offset:3072
	ds_read_b128 v[26:29], v224 offset:32768
	ds_read_b128 v[30:33], v224 offset:33792
	ds_read_b128 v[62:65], v224 offset:34816
	ds_read_b128 v[114:117], v224 offset:35840
	ds_read_b128 v[236:239], v224 offset:36864
	ds_read_b128 v[240:243], v224 offset:37888
	ds_read_b128 v[244:247], v224 offset:38912
	ds_read_b128 v[248:251], v224 offset:39936
	s_add_u32 s26, s30, 0x40100
	s_addc_u32 s27, s31, 0
	s_add_u32 m0, s14, 0x4000
	s_nop 0
	global_load_lds_dwordx4 v1, s[26:27]
	s_nop 0
	s_add_u32 m0, s14, 0x6000
	s_nop 0
	global_load_lds_dwordx4 v213, s[26:27]
	s_waitcnt vmcnt(8)
	s_waitcnt lgkmcnt(0)
	s_barrier
	v_mfma_f32_16x16x32_f16 v[66:69], v[10:13], v[26:29], v[66:69]
	s_setprio 1
	v_mfma_f32_16x16x32_f16 v[154:157], v[14:17], v[30:33], v[66:69]
	v_mfma_f32_16x16x32_f16 v[66:69], v[18:21], v[26:29], v[70:73]
	v_mfma_f32_16x16x32_f16 v[150:153], v[22:25], v[30:33], v[66:69]
	v_mfma_f32_16x16x32_f16 v[66:69], v[10:13], v[62:65], v[74:77]
	v_mfma_f32_16x16x32_f16 v[130:133], v[14:17], v[114:117], v[66:69]
	v_mfma_f32_16x16x32_f16 v[66:69], v[18:21], v[62:65], v[78:81]
	v_mfma_f32_16x16x32_f16 v[126:129], v[22:25], v[114:117], v[66:69]
	v_mfma_f32_16x16x32_f16 v[66:69], v[10:13], v[236:239], v[82:85]
	v_mfma_f32_16x16x32_f16 v[106:109], v[14:17], v[240:243], v[66:69]
	v_mfma_f32_16x16x32_f16 v[66:69], v[18:21], v[236:239], v[86:89]
	v_mfma_f32_16x16x32_f16 v[102:105], v[22:25], v[240:243], v[66:69]
	v_mfma_f32_16x16x32_f16 v[66:69], v[10:13], v[244:247], v[90:93]
	v_mfma_f32_16x16x32_f16 v[82:85], v[14:17], v[248:251], v[66:69]
	v_mfma_f32_16x16x32_f16 v[66:69], v[18:21], v[244:247], v[94:97]
	v_mfma_f32_16x16x32_f16 v[78:81], v[22:25], v[248:251], v[66:69]
	v_mfma_f32_16x16x32_f16 v[66:69], v[198:201], v[26:29], v[98:101]
	v_mfma_f32_16x16x32_f16 v[142:145], v[214:217], v[30:33], v[66:69]
	v_mfma_f32_16x16x32_f16 v[26:29], v[228:231], v[26:29], v[34:37]
	v_mfma_f32_16x16x32_f16 v[138:141], v[232:235], v[30:33], v[26:29]
	v_mfma_f32_16x16x32_f16 v[26:29], v[198:201], v[62:65], v[38:41]
	v_mfma_f32_16x16x32_f16 v[118:121], v[214:217], v[114:117], v[26:29]
	v_mfma_f32_16x16x32_f16 v[26:29], v[228:231], v[62:65], v[42:45]
	v_mfma_f32_16x16x32_f16 v[114:117], v[232:235], v[114:117], v[26:29]
	v_mfma_f32_16x16x32_f16 v[26:29], v[198:201], v[236:239], v[46:49]
	v_mfma_f32_16x16x32_f16 v[94:97], v[214:217], v[240:243], v[26:29]
	v_mfma_f32_16x16x32_f16 v[26:29], v[228:231], v[236:239], v[50:53]
	v_mfma_f32_16x16x32_f16 v[90:93], v[232:235], v[240:243], v[26:29]
	v_mfma_f32_16x16x32_f16 v[26:29], v[198:201], v[244:247], v[54:57]
	v_mfma_f32_16x16x32_f16 v[70:73], v[214:217], v[248:251], v[26:29]
	v_mfma_f32_16x16x32_f16 v[26:29], v[228:231], v[244:247], v[58:61]
	v_mfma_f32_16x16x32_f16 v[66:69], v[232:235], v[248:251], v[26:29]
	s_barrier
	s_setprio 0
	ds_read_b128 v[34:37], v224 offset:49152
	ds_read_b128 v[38:41], v224 offset:50176
	ds_read_b128 v[74:77], v224 offset:51200
	ds_read_b128 v[86:89], v224 offset:52224
	ds_read_b128 v[98:101], v224 offset:53248
	ds_read_b128 v[236:239], v224 offset:54272
	ds_read_b128 v[240:243], v224 offset:55296
	ds_read_b128 v[244:247], v224 offset:56320
	s_add_u32 m0, s14, 0x18000
	s_nop 0
	global_load_lds_dwordx4 v209, s[24:25]
	s_nop 0
	s_add_u32 m0, s14, 0x1a000
	s_nop 0
	global_load_lds_dwordx4 v219, s[24:25]
	s_add_u32 s24, s6, 0x40180
	s_addc_u32 s25, s7, 0
	s_add_u32 m0, s14, 0x1c000
	s_nop 0
	global_load_lds_dwordx4 v209, s[24:25]
	s_nop 0
	s_add_u32 m0, s14, 0x1e000
	s_nop 0
	global_load_lds_dwordx4 v219, s[24:25]
	s_nop 0
	s_add_u32 m0, s14, 0x8000
	s_nop 0
	global_load_lds_dwordx4 v1, s[8:9]
	s_nop 0
	s_add_u32 m0, s14, 0xa000
	s_nop 0
	global_load_lds_dwordx4 v213, s[8:9]
	s_waitcnt vmcnt(8)
	s_waitcnt lgkmcnt(0)
	s_barrier
	v_mfma_f32_16x16x32_f16 v[26:29], v[10:13], v[34:37], v[134:137]
	s_setprio 1
	v_mfma_f32_16x16x32_f16 v[62:65], v[14:17], v[38:41], v[26:29]
	v_mfma_f32_16x16x32_f16 v[26:29], v[22:25], v[38:41], v[146:149]
	v_mfma_f32_16x16x32_f16 v[58:61], v[18:21], v[34:37], v[26:29]
	v_mfma_f32_16x16x32_f16 v[26:29], v[10:13], v[74:77], v[158:161]
	v_mfma_f32_16x16x32_f16 v[46:49], v[14:17], v[86:89], v[26:29]
	v_mfma_f32_16x16x32_f16 v[26:29], v[22:25], v[86:89], v[162:165]
	v_mfma_f32_16x16x32_f16 v[42:45], v[18:21], v[74:77], v[26:29]
	v_mfma_f32_16x16x32_f16 v[26:29], v[10:13], v[98:101], v[166:169]
	v_mfma_f32_16x16x32_f16 v[30:33], v[14:17], v[236:239], v[26:29]
	v_mfma_f32_16x16x32_f16 v[26:29], v[22:25], v[236:239], v[170:173]
	v_mfma_f32_16x16x32_f16 v[26:29], v[18:21], v[98:101], v[26:29]
	v_mfma_f32_16x16x32_f16 v[2:5], v[10:13], v[240:243], v[2:5]
	v_mfma_f32_16x16x32_f16 v[14:17], v[14:17], v[244:247], v[2:5]
	v_mfma_f32_16x16x32_f16 v[2:5], v[22:25], v[244:247], v[6:9]
	v_mfma_f32_16x16x32_f16 v[10:13], v[18:21], v[240:243], v[2:5]
	v_mfma_f32_16x16x32_f16 v[2:5], v[198:201], v[34:37], v[174:177]
	v_mfma_f32_16x16x32_f16 v[54:57], v[214:217], v[38:41], v[2:5]
	v_mfma_f32_16x16x32_f16 v[2:5], v[232:235], v[38:41], v[178:181]
	v_mfma_f32_16x16x32_f16 v[50:53], v[228:231], v[34:37], v[2:5]
	v_mfma_f32_16x16x32_f16 v[2:5], v[198:201], v[74:77], v[182:185]
	v_mfma_f32_16x16x32_f16 v[38:41], v[214:217], v[86:89], v[2:5]
	v_mfma_f32_16x16x32_f16 v[2:5], v[232:235], v[86:89], v[110:113]
	v_mfma_f32_16x16x32_f16 v[34:37], v[228:231], v[74:77], v[2:5]
	v_mfma_f32_16x16x32_f16 v[2:5], v[198:201], v[98:101], v[186:189]
	v_mfma_f32_16x16x32_f16 v[22:25], v[214:217], v[236:239], v[2:5]
	v_mfma_f32_16x16x32_f16 v[2:5], v[232:235], v[236:239], v[190:193]
	v_mfma_f32_16x16x32_f16 v[18:21], v[228:231], v[98:101], v[2:5]
	v_mfma_f32_16x16x32_f16 v[2:5], v[198:201], v[240:243], v[194:197]
	v_mfma_f32_16x16x32_f16 v[6:9], v[214:217], v[244:247], v[2:5]
	v_mfma_f32_16x16x32_f16 v[2:5], v[232:235], v[244:247], v[122:125]
	v_mfma_f32_16x16x32_f16 v[2:5], v[228:231], v[240:243], v[2:5]
	s_barrier
	s_setprio 0
	s_add_u32 s30, s6, 0x200
	s_addc_u32 s31, s7, 0
	s_mov_b32 s59, 0
	s_branch .LBB0_750

;     __device__ __forceinline__ bool next(int i, Unit& u) const { if (i >= count) return false; const int L = first + i; u.pm = L / nN; u.pn = L % nN; return true; }
; #define PG8_STAGE(bufoff, gbase, voff) do { if constexpr (ABL & 1) break; glds16s<(bufoff)>((voff)[0], (const void*)(gbase), ldsbw); glds16s<(bufoff) + 8192>((voff)[1], (const void*)(gbase), ldsbw); } while (0)
; #define PG8_LDA(dst, b, h) do { if constexpr (ABL & 4) break; _Pragma("unroll") for (int m = 0; m < 4; ++m) _Pragma("unroll") for (int k = 0; k < 2; ++k) dst[m][k] = *(const LAS f16x8*)(lds + PG8_SA(b, h) + aoff + m * 2048 + k * 1024); } while (0)
; #define PG8_LDB(dst, b, h) do { if constexpr (ABL & 4) break; _Pragma("unroll") for (int n = 0; n < 2; ++n) _Pragma("unroll") for (int k = 0; k < 2; ++k) dst[n][k] = *(const LAS f16x8*)(lds + PG8_SB(b, h) + boff + n * 2048 + k * 1024); } while (0)
; #define PG8_MMAF(ai, bj, At, Bt) do { if (t == 0) PG8_MMA0(ai, bj, At, Bt); else PG8_MMA(ai, bj, At, Bt); } while (0)
; #define PG8_WAIT_V(n) asm volatile("s_waitcnt vmcnt(" #n ")" ::: "memory")
; #define PG8_BAR __builtin_amdgcn_s_barrier()
;     ...
;         const bool has_next = S.next(ui + 1, nxt);
;         const char* nA = has_next ? (const char*)g.A + (size_t)nxt.pm * tstep : cA; const char* nB = has_next ? (const char*)g.Bt + (size_t)nxt.pn * tstep : cB;
;         for (int t = 0; t < nt; t += 2) {
;             const bool last = (t == nt - 2);
;             const char* a1 = cA + (size_t)(t + 1) * kstep;
;             const char* a2 = last ? nA : cA + (size_t)(t + 2) * kstep; const char* b2 = last ? nB : cB + (size_t)(t + 2) * kstep;
;             const char* a3 = a2 + kstep; const char* b3 = b2 + kstep;
;             if (last && has_next) S.a_ready(nxt);
;             if constexpr (SP2) {
;             PG8_LDB(B0, 0, 0); PG8_LDB(B1, 0, 1); PG8_SCHED; PG8_LDA(At, 0, 0); PG8_STAGE(PG8_SA(1, 1), a1 + hstep, voffA);
;             PG8_WAIT_V(8); PG8_WAIT_L(0); PG8_BAR; PG8_MMAF(0, 0, At, B0); PG8_MMAF(0, 1, At, B1); PG8_BAR; PG8_SCHED;
;             const bool fin = last && !has_next;
;             PG8_LDA(At, 0, 1); if (!fin) { PG8_STAGE(PG8_SB(0, 0), b2, voffB); PG8_STAGE(PG8_SB(0, 1), b2 + hstep, voffB); PG8_STAGE(PG8_SA(0, 0), a2, voffA); }
;             if (!fin) PG8_WAIT_V(8); else PG8_WAIT_V(2); PG8_WAIT_L(0); PG8_BAR; PG8_MMAF(1, 0, At, B0); PG8_MMAF(1, 1, At, B1); PG8_BAR; PG8_SCHED;
.LBB0_841:
	s_ashr_i32 s41, s40, 31
	s_lshl_b64 s[24:25], s[40:41], 19
	s_add_u32 s42, s74, s24
	s_addc_u32 s43, s75, s25
	s_and_b64 s[24:25], exec, s[4:5]
	ds_read_b128 v[2:5], v210
	ds_read_b128 v[6:9], v210 offset:1024
	ds_read_b128 v[10:13], v210 offset:2048
	ds_read_b128 v[14:17], v210 offset:3072
	ds_read_b128 v[18:21], v211
	ds_read_b128 v[22:25], v211 offset:1024
	ds_read_b128 v[26:29], v211 offset:2048
	ds_read_b128 v[30:33], v211 offset:3072
	s_cselect_b32 s41, s9, s43
	s_cselect_b32 s51, s8, s42
	s_ashr_i32 s39, s38, 31
	s_lshl_b64 s[24:25], s[38:39], 19
	s_add_u32 s44, s58, s24
	s_addc_u32 s45, s59, s25
	s_and_b64 s[24:25], exec, s[4:5]
	s_cselect_b32 s39, s7, s45
	s_cselect_b32 s52, s6, s44
	s_add_u32 s48, s8, 0x100
	s_addc_u32 s49, s9, 0
	s_add_u32 s54, s6, 0x100
	s_addc_u32 s55, s7, 0
	s_add_u32 s24, s8, 0x180
	s_addc_u32 s25, s9, 0
	ds_read_b128 v[34:37], v212
	ds_read_b128 v[38:41], v212 offset:1024
	ds_read_b128 v[42:45], v212 offset:2048
	ds_read_b128 v[46:49], v212 offset:3072
	ds_read_b128 v[50:53], v212 offset:4096
	ds_read_b128 v[54:57], v212 offset:5120
	ds_read_b128 v[58:61], v212 offset:6144
	ds_read_b128 v[62:65], v212 offset:7168
	s_add_u32 s26, s6, 0x180
	s_addc_u32 s27, s7, 0
	s_add_u32 s56, s8, 0x40080
	s_addc_u32 s57, s9, 0
	s_add_u32 m0, s14, 0xc000
	s_nop 0
	global_load_lds_dwordx4 v206, s[56:57]
	s_nop 0
	s_add_u32 m0, s14, 0xe000
	s_nop 0
	global_load_lds_dwordx4 v208, s[56:57]
	s_waitcnt vmcnt(8)
	s_waitcnt lgkmcnt(0)
	s_barrier
	v_mfma_f32_16x16x32_f16 v[90:93], v[2:5], v[58:61], 0
	s_setprio 1
	v_mfma_f32_16x16x32_f16 v[94:97], v[6:9], v[62:65], v[90:93]
	v_mfma_f32_16x16x32_f16 v[66:69], v[6:9], v[38:41], 0
	v_mfma_f32_16x16x32_f16 v[66:69], v[2:5], v[34:37], v[66:69]
	v_mfma_f32_16x16x32_f16 v[70:73], v[10:13], v[34:37], 0
	v_mfma_f32_16x16x32_f16 v[70:73], v[14:17], v[38:41], v[70:73]
	v_mfma_f32_16x16x32_f16 v[78:81], v[14:17], v[46:49], 0
	v_mfma_f32_16x16x32_f16 v[78:81], v[10:13], v[42:45], v[78:81]
	v_mfma_f32_16x16x32_f16 v[74:77], v[2:5], v[42:45], 0
	v_mfma_f32_16x16x32_f16 v[74:77], v[6:9], v[46:49], v[74:77]
	v_mfma_f32_16x16x32_f16 v[82:85], v[6:9], v[54:57], 0
	v_mfma_f32_16x16x32_f16 v[82:85], v[2:5], v[50:53], v[82:85]
	v_mfma_f32_16x16x32_f16 v[86:89], v[10:13], v[50:53], 0
	v_mfma_f32_16x16x32_f16 v[86:89], v[14:17], v[54:57], v[86:89]
	v_mfma_f32_16x16x32_f16 v[90:93], v[14:17], v[62:65], 0
	v_mfma_f32_16x16x32_f16 v[102:105], v[10:13], v[58:61], v[90:93]
	v_mfma_f32_16x16x32_f16 v[90:93], v[18:21], v[34:37], 0
	v_mfma_f32_16x16x32_f16 v[118:121], v[22:25], v[38:41], v[90:93]
	v_mfma_f32_16x16x32_f16 v[34:37], v[26:29], v[34:37], 0
	v_mfma_f32_16x16x32_f16 v[34:37], v[30:33], v[38:41], v[34:37]
	v_mfma_f32_16x16x32_f16 v[38:41], v[18:21], v[42:45], 0
	v_mfma_f32_16x16x32_f16 v[38:41], v[22:25], v[46:49], v[38:41]
	v_mfma_f32_16x16x32_f16 v[42:45], v[26:29], v[42:45], 0
	v_mfma_f32_16x16x32_f16 v[42:45], v[30:33], v[46:49], v[42:45]
	v_mfma_f32_16x16x32_f16 v[46:49], v[18:21], v[50:53], 0
	v_mfma_f32_16x16x32_f16 v[46:49], v[22:25], v[54:57], v[46:49]
	v_mfma_f32_16x16x32_f16 v[50:53], v[26:29], v[50:53], 0
	v_mfma_f32_16x16x32_f16 v[50:53], v[30:33], v[54:57], v[50:53]
	v_mfma_f32_16x16x32_f16 v[54:57], v[18:21], v[58:61], 0
	v_mfma_f32_16x16x32_f16 v[54:57], v[22:25], v[62:65], v[54:57]
	v_mfma_f32_16x16x32_f16 v[58:61], v[26:29], v[58:61], 0
	v_mfma_f32_16x16x32_f16 v[58:61], v[30:33], v[62:65], v[58:61]
	s_barrier
	s_setprio 0
	ds_read_b128 v[62:65], v212 offset:16384
	ds_read_b128 v[90:93], v212 offset:17408
	ds_read_b128 v[98:101], v212 offset:18432
	ds_read_b128 v[106:109], v212 offset:19456
	ds_read_b128 v[110:113], v212 offset:20480
	ds_read_b128 v[114:117], v212 offset:21504
	ds_read_b128 v[122:125], v212 offset:22528
	ds_read_b128 v[126:129], v212 offset:23552
	s_add_u32 m0, s14, 0x10000
	s_nop 0
	global_load_lds_dwordx4 v207, s[54:55]
	s_nop 0
	s_add_u32 m0, s14, 0x12000
	s_nop 0
	global_load_lds_dwordx4 v209, s[54:55]
	s_add_u32 s54, s6, 0x40100
	s_addc_u32 s55, s7, 0
	s_add_u32 m0, s14, 0x14000
	s_nop 0
	global_load_lds_dwordx4 v207, s[54:55]
	s_nop 0
	s_add_u32 m0, s14, 0x16000
	s_nop 0
	global_load_lds_dwordx4 v209, s[54:55]
	s_nop 0
	s_add_u32 m0, s14, 0
	s_nop 0
	global_load_lds_dwordx4 v206, s[48:49]
	s_nop 0
	s_add_u32 m0, s14, 0x2000
	s_nop 0
	global_load_lds_dwordx4 v208, s[48:49]
	s_waitcnt vmcnt(8)
	s_waitcnt lgkmcnt(0)
	s_barrier
	v_mfma_f32_16x16x32_f16 v[130:133], v[2:5], v[62:65], 0
	s_setprio 1
	v_mfma_f32_16x16x32_f16 v[130:133], v[6:9], v[90:93], v[130:133]
	v_mfma_f32_16x16x32_f16 v[138:141], v[2:5], v[98:101], 0
	v_mfma_f32_16x16x32_f16 v[138:141], v[6:9], v[106:109], v[138:141]
	v_mfma_f32_16x16x32_f16 v[146:149], v[2:5], v[110:113], 0
	v_mfma_f32_16x16x32_f16 v[146:149], v[6:9], v[114:117], v[146:149]
	v_mfma_f32_16x16x32_f16 v[2:5], v[2:5], v[122:125], 0
	v_mfma_f32_16x16x32_f16 v[2:5], v[6:9], v[126:129], v[2:5]
	v_mfma_f32_16x16x32_f16 v[6:9], v[10:13], v[122:125], 0
	v_mfma_f32_16x16x32_f16 v[6:9], v[14:17], v[126:129], v[6:9]
	v_mfma_f32_16x16x32_f16 v[134:137], v[10:13], v[62:65], 0
	v_mfma_f32_16x16x32_f16 v[134:137], v[14:17], v[90:93], v[134:137]
	v_mfma_f32_16x16x32_f16 v[142:145], v[10:13], v[98:101], 0
	v_mfma_f32_16x16x32_f16 v[142:145], v[14:17], v[106:109], v[142:145]
	v_mfma_f32_16x16x32_f16 v[150:153], v[10:13], v[110:113], 0
	v_mfma_f32_16x16x32_f16 v[150:153], v[14:17], v[114:117], v[150:153]
	v_mfma_f32_16x16x32_f16 v[10:13], v[18:21], v[62:65], 0
	v_mfma_f32_16x16x32_f16 v[14:17], v[22:25], v[90:93], v[10:13]
	v_mfma_f32_16x16x32_f16 v[10:13], v[26:29], v[62:65], 0
	v_mfma_f32_16x16x32_f16 v[154:157], v[30:33], v[90:93], v[10:13]
	v_mfma_f32_16x16x32_f16 v[10:13], v[18:21], v[98:101], 0
	v_mfma_f32_16x16x32_f16 v[158:161], v[22:25], v[106:109], v[10:13]
	v_mfma_f32_16x16x32_f16 v[10:13], v[26:29], v[98:101], 0
	v_mfma_f32_16x16x32_f16 v[162:165], v[30:33], v[106:109], v[10:13]
	v_mfma_f32_16x16x32_f16 v[10:13], v[18:21], v[110:113], 0
	v_mfma_f32_16x16x32_f16 v[166:169], v[22:25], v[114:117], v[10:13]
	v_mfma_f32_16x16x32_f16 v[10:13], v[26:29], v[110:113], 0
	v_mfma_f32_16x16x32_f16 v[170:173], v[30:33], v[114:117], v[10:13]
	v_mfma_f32_16x16x32_f16 v[10:13], v[18:21], v[122:125], 0
	v_mfma_f32_16x16x32_f16 v[174:177], v[22:25], v[126:129], v[10:13]
	v_mfma_f32_16x16x32_f16 v[10:13], v[26:29], v[122:125], 0
	v_mfma_f32_16x16x32_f16 v[178:181], v[30:33], v[126:129], v[10:13]
	s_barrier
; #define PG8_STAGE(bufoff, gbase, voff) do { if constexpr (ABL & 1) break; glds16s<(bufoff)>((voff)[0], (const void*)(gbase), ldsbw); glds16s<(bufoff) + 8192>((voff)[1], (const void*)(gbase), ldsbw); } while (0)
; #define PG8_LDA(dst, b, h) do { if constexpr (ABL & 4) break; _Pragma("unroll") for (int m = 0; m < 4; ++m) _Pragma("unroll") for (int k = 0; k < 2; ++k) dst[m][k] = *(const LAS f16x8*)(lds + PG8_SA(b, h) + aoff + m * 2048 + k * 1024); } while (0)
; #define PG8_LDB(dst, b, h) do { if constexpr (ABL & 4) break; _Pragma("unroll") for (int n = 0; n < 2; ++n) _Pragma("unroll") for (int k = 0; k < 2; ++k) dst[n][k] = *(const LAS f16x8*)(lds + PG8_SB(b, h) + boff + n * 2048 + k * 1024); } while (0)
; #define PG8_MMA(ai, bj, At, Bt) do { if constexpr (ABL & 2) break; __builtin_amdgcn_s_setprio(1); _Pragma("unroll") for (int m = 0; m < 4; ++m) _Pragma("unroll") for (int n = 0; n < 2; ++n) _Pragma("unroll") for (int k = 0; k < 2; ++k) \
;         acc[ai][bj][m][n] = __builtin_amdgcn_mfma_f32_16x16x32_f16(Bt[n][k], At[m][k], acc[ai][bj][m][n], 0, 0, 0); __builtin_amdgcn_s_setprio(0); } while (0)
; #define PG8_WAIT_V(n) asm volatile("s_waitcnt vmcnt(" #n ")" ::: "memory")
; #define PG8_WAIT_L(n) asm volatile("s_waitcnt lgkmcnt(" #n ")" ::: "memory")
; #define PG8_BAR __builtin_amdgcn_s_barrier()
; #define PG8_SCHED __builtin_amdgcn_sched_barrier(0)
;     ...
;             PG8_LDB(B0, 1, 0); PG8_LDB(B1, 1, 1); PG8_SCHED; PG8_LDA(At, 1, 0); if (!fin) PG8_STAGE(PG8_SA(0, 1), a2 + hstep, voffA);
;             if (!fin) PG8_WAIT_V(8); else PG8_WAIT_V(0); PG8_WAIT_L(0); PG8_BAR; PG8_MMA(0, 0, At, B0); PG8_MMA(0, 1, At, B1); PG8_BAR; PG8_SCHED;
;             PG8_LDA(At, 1, 1); if (!fin) { PG8_STAGE(PG8_SB(1, 0), b3, voffB); PG8_STAGE(PG8_SB(1, 1), b3 + hstep, voffB); PG8_STAGE(PG8_SA(1, 0), a3, voffA); }
;             if (!fin) PG8_WAIT_V(8); PG8_WAIT_L(0); PG8_BAR; PG8_MMA(1, 0, At, B0); PG8_MMA(1, 1, At, B1); PG8_BAR; PG8_SCHED;
	s_setprio 0
	s_nop 4
	ds_read_b128 v[10:13], v213
	ds_read_b128 v[22:25], v213 offset:1024
	ds_read_b128 v[30:33], v213 offset:2048
	ds_read_b128 v[182:185], v213 offset:3072
	ds_read_b128 v[186:189], v214
	ds_read_b128 v[190:193], v214 offset:1024
	ds_read_b128 v[216:219], v214 offset:2048
	ds_read_b128 v[220:223], v214 offset:3072
	ds_read_b128 v[18:21], v212 offset:32768
	ds_read_b128 v[26:29], v212 offset:33792
	ds_read_b128 v[224:227], v212 offset:34816
	ds_read_b128 v[228:231], v212 offset:35840
	ds_read_b128 v[232:235], v212 offset:36864
	ds_read_b128 v[236:239], v212 offset:37888
	ds_read_b128 v[240:243], v212 offset:38912
	ds_read_b128 v[244:247], v212 offset:39936
	s_add_u32 s8, s8, 0x40100
	s_addc_u32 s9, s9, 0
	s_add_u32 m0, s14, 0x4000
	s_nop 0
	global_load_lds_dwordx4 v206, s[8:9]
	s_nop 0
	s_add_u32 m0, s14, 0x6000
	s_nop 0
	global_load_lds_dwordx4 v208, s[8:9]
	s_waitcnt vmcnt(8)
	s_waitcnt lgkmcnt(0)
	s_barrier
	v_mfma_f32_16x16x32_f16 v[62:65], v[10:13], v[18:21], v[66:69]
	s_setprio 1
	v_mfma_f32_16x16x32_f16 v[114:117], v[22:25], v[26:29], v[62:65]
	v_mfma_f32_16x16x32_f16 v[62:65], v[30:33], v[18:21], v[70:73]
	v_mfma_f32_16x16x32_f16 v[110:113], v[182:185], v[26:29], v[62:65]
	v_mfma_f32_16x16x32_f16 v[62:65], v[10:13], v[224:227], v[74:77]
	v_mfma_f32_16x16x32_f16 v[106:109], v[22:25], v[228:231], v[62:65]
	v_mfma_f32_16x16x32_f16 v[62:65], v[30:33], v[224:227], v[78:81]
	v_mfma_f32_16x16x32_f16 v[98:101], v[182:185], v[228:231], v[62:65]
	v_mfma_f32_16x16x32_f16 v[62:65], v[10:13], v[232:235], v[82:85]
	v_mfma_f32_16x16x32_f16 v[90:93], v[22:25], v[236:239], v[62:65]
	v_mfma_f32_16x16x32_f16 v[62:65], v[30:33], v[232:235], v[86:89]
	v_mfma_f32_16x16x32_f16 v[82:85], v[182:185], v[236:239], v[62:65]
	v_mfma_f32_16x16x32_f16 v[62:65], v[10:13], v[240:243], v[94:97]
	v_mfma_f32_16x16x32_f16 v[74:77], v[22:25], v[244:247], v[62:65]
	v_mfma_f32_16x16x32_f16 v[62:65], v[30:33], v[240:243], v[102:105]
	v_mfma_f32_16x16x32_f16 v[62:65], v[182:185], v[244:247], v[62:65]
	v_mfma_f32_16x16x32_f16 v[66:69], v[186:189], v[18:21], v[118:121]
	v_mfma_f32_16x16x32_f16 v[126:129], v[190:193], v[26:29], v[66:69]
	v_mfma_f32_16x16x32_f16 v[18:21], v[216:219], v[18:21], v[34:37]
	v_mfma_f32_16x16x32_f16 v[122:125], v[220:223], v[26:29], v[18:21]
	v_mfma_f32_16x16x32_f16 v[18:21], v[186:189], v[224:227], v[38:41]
	v_mfma_f32_16x16x32_f16 v[118:121], v[190:193], v[228:231], v[18:21]
	v_mfma_f32_16x16x32_f16 v[18:21], v[216:219], v[224:227], v[42:45]
	v_mfma_f32_16x16x32_f16 v[102:105], v[220:223], v[228:231], v[18:21]
	v_mfma_f32_16x16x32_f16 v[18:21], v[186:189], v[232:235], v[46:49]
	v_mfma_f32_16x16x32_f16 v[94:97], v[190:193], v[236:239], v[18:21]
	v_mfma_f32_16x16x32_f16 v[18:21], v[216:219], v[232:235], v[50:53]
	v_mfma_f32_16x16x32_f16 v[86:89], v[220:223], v[236:239], v[18:21]
	v_mfma_f32_16x16x32_f16 v[18:21], v[186:189], v[240:243], v[54:57]
	v_mfma_f32_16x16x32_f16 v[78:81], v[190:193], v[244:247], v[18:21]
	v_mfma_f32_16x16x32_f16 v[18:21], v[216:219], v[240:243], v[58:61]
	v_mfma_f32_16x16x32_f16 v[70:73], v[220:223], v[244:247], v[18:21]
	s_barrier
	s_setprio 0
	ds_read_b128 v[38:41], v212 offset:49152
	ds_read_b128 v[46:49], v212 offset:50176
	ds_read_b128 v[224:227], v212 offset:51200
	ds_read_b128 v[228:231], v212 offset:52224
	ds_read_b128 v[232:235], v212 offset:53248
	ds_read_b128 v[236:239], v212 offset:54272
	ds_read_b128 v[240:243], v212 offset:55296
	ds_read_b128 v[244:247], v212 offset:56320
	s_add_u32 m0, s14, 0x18000
	s_nop 0
	global_load_lds_dwordx4 v207, s[26:27]
	s_nop 0
	s_add_u32 m0, s14, 0x1a000
	s_nop 0
	global_load_lds_dwordx4 v209, s[26:27]
	s_add_u32 s8, s6, 0x40180
	s_addc_u32 s9, s7, 0
	s_add_u32 m0, s14, 0x1c000
	s_nop 0
	global_load_lds_dwordx4 v207, s[8:9]
	s_nop 0
	s_add_u32 m0, s14, 0x1e000
	s_nop 0
	global_load_lds_dwordx4 v209, s[8:9]
	s_nop 0
	s_add_u32 m0, s14, 0x8000
	s_nop 0
	global_load_lds_dwordx4 v206, s[24:25]
	s_nop 0
	s_add_u32 m0, s14, 0xa000
	s_nop 0
	global_load_lds_dwordx4 v208, s[24:25]
	s_waitcnt vmcnt(8)
	s_waitcnt lgkmcnt(0)
	s_barrier
	v_mfma_f32_16x16x32_f16 v[18:21], v[10:13], v[38:41], v[130:133]
	s_setprio 1
	v_mfma_f32_16x16x32_f16 v[58:61], v[22:25], v[46:49], v[18:21]
	v_mfma_f32_16x16x32_f16 v[18:21], v[182:185], v[46:49], v[134:137]
	v_mfma_f32_16x16x32_f16 v[50:53], v[30:33], v[38:41], v[18:21]
	v_mfma_f32_16x16x32_f16 v[18:21], v[10:13], v[224:227], v[138:141]
	v_mfma_f32_16x16x32_f16 v[42:45], v[22:25], v[228:231], v[18:21]
	v_mfma_f32_16x16x32_f16 v[18:21], v[182:185], v[228:231], v[142:145]
	v_mfma_f32_16x16x32_f16 v[34:37], v[30:33], v[224:227], v[18:21]
	v_mfma_f32_16x16x32_f16 v[18:21], v[10:13], v[232:235], v[146:149]
	v_mfma_f32_16x16x32_f16 v[26:29], v[22:25], v[236:239], v[18:21]
	v_mfma_f32_16x16x32_f16 v[18:21], v[182:185], v[236:239], v[150:153]
	v_mfma_f32_16x16x32_f16 v[18:21], v[30:33], v[232:235], v[18:21]
	v_mfma_f32_16x16x32_f16 v[2:5], v[10:13], v[240:243], v[2:5]
	v_mfma_f32_16x16x32_f16 v[10:13], v[22:25], v[244:247], v[2:5]
	v_mfma_f32_16x16x32_f16 v[2:5], v[182:185], v[244:247], v[6:9]
	v_mfma_f32_16x16x32_f16 v[2:5], v[30:33], v[240:243], v[2:5]
	v_mfma_f32_16x16x32_f16 v[6:9], v[186:189], v[38:41], v[14:17]
	v_mfma_f32_16x16x32_f16 v[66:69], v[190:193], v[46:49], v[6:9]
	v_mfma_f32_16x16x32_f16 v[6:9], v[220:223], v[46:49], v[154:157]
	v_mfma_f32_16x16x32_f16 v[54:57], v[216:219], v[38:41], v[6:9]
	v_mfma_f32_16x16x32_f16 v[6:9], v[186:189], v[224:227], v[158:161]
	v_mfma_f32_16x16x32_f16 v[46:49], v[190:193], v[228:231], v[6:9]
	v_mfma_f32_16x16x32_f16 v[6:9], v[220:223], v[228:231], v[162:165]
	v_mfma_f32_16x16x32_f16 v[38:41], v[216:219], v[224:227], v[6:9]
	v_mfma_f32_16x16x32_f16 v[6:9], v[186:189], v[232:235], v[166:169]
	v_mfma_f32_16x16x32_f16 v[30:33], v[190:193], v[236:239], v[6:9]
	v_mfma_f32_16x16x32_f16 v[6:9], v[220:223], v[236:239], v[170:173]
	v_mfma_f32_16x16x32_f16 v[22:25], v[216:219], v[232:235], v[6:9]
	v_mfma_f32_16x16x32_f16 v[6:9], v[186:189], v[240:243], v[174:177]
	v_mfma_f32_16x16x32_f16 v[14:17], v[190:193], v[244:247], v[6:9]
	v_mfma_f32_16x16x32_f16 v[6:9], v[220:223], v[244:247], v[178:181]
	v_mfma_f32_16x16x32_f16 v[6:9], v[216:219], v[240:243], v[6:9]
	s_barrier
	s_setprio 0
	s_add_u32 s53, s6, 0x200
	s_addc_u32 s54, s7, 0
	s_mov_b32 s55, 0
	s_branch .LBB0_843

;     __device__ __forceinline__ bool next(int i, Unit& u) const { if (i >= count) return false; const int L = first + i; u.pm = L / nN; u.pn = L % nN; return true; }
; #define PG8_STAGE(bufoff, gbase, voff) do { if constexpr (ABL & 1) break; glds16s<(bufoff)>((voff)[0], (const void*)(gbase), ldsbw); glds16s<(bufoff) + 8192>((voff)[1], (const void*)(gbase), ldsbw); } while (0)
; #define PG8_LDA(dst, b, h) do { if constexpr (ABL & 4) break; _Pragma("unroll") for (int m = 0; m < 4; ++m) _Pragma("unroll") for (int k = 0; k < 2; ++k) dst[m][k] = *(const LAS f16x8*)(lds + PG8_SA(b, h) + aoff + m * 2048 + k * 1024); } while (0)
; #define PG8_LDB(dst, b, h) do { if constexpr (ABL & 4) break; _Pragma("unroll") for (int n = 0; n < 2; ++n) _Pragma("unroll") for (int k = 0; k < 2; ++k) dst[n][k] = *(const LAS f16x8*)(lds + PG8_SB(b, h) + boff + n * 2048 + k * 1024); } while (0)
; #define PG8_MMAF(ai, bj, At, Bt) do { if (t == 0) PG8_MMA0(ai, bj, At, Bt); else PG8_MMA(ai, bj, At, Bt); } while (0)
; #define PG8_WAIT_V(n) asm volatile("s_waitcnt vmcnt(" #n ")" ::: "memory")
; #define PG8_BAR __builtin_amdgcn_s_barrier()
;     ...
;         const bool has_next = S.next(ui + 1, nxt);
;         const char* nA = has_next ? (const char*)g.A + (size_t)nxt.pm * tstep : cA; const char* nB = has_next ? (const char*)g.Bt + (size_t)nxt.pn * tstep : cB;
;         for (int t = 0; t < nt; t += 2) {
;             const bool last = (t == nt - 2);
;             const char* a1 = cA + (size_t)(t + 1) * kstep;
;             const char* a2 = last ? nA : cA + (size_t)(t + 2) * kstep; const char* b2 = last ? nB : cB + (size_t)(t + 2) * kstep;
;             const char* a3 = a2 + kstep; const char* b3 = b2 + kstep;
;             if (last && has_next) S.a_ready(nxt);
;             if constexpr (SP2) {
;             PG8_LDB(B0, 0, 0); PG8_LDB(B1, 0, 1); PG8_SCHED; PG8_LDA(At, 0, 0); PG8_STAGE(PG8_SA(1, 1), a1 + hstep, voffA);
;             PG8_WAIT_V(8); PG8_WAIT_L(0); PG8_BAR; PG8_MMAF(0, 0, At, B0); PG8_MMAF(0, 1, At, B1); PG8_BAR; PG8_SCHED;
;             const bool fin = last && !has_next;
;             PG8_LDA(At, 0, 1); if (!fin) { PG8_STAGE(PG8_SB(0, 0), b2, voffB); PG8_STAGE(PG8_SB(0, 1), b2 + hstep, voffB); PG8_STAGE(PG8_SA(0, 0), a2, voffA); }
;             if (!fin) PG8_WAIT_V(8); else PG8_WAIT_V(2); PG8_WAIT_L(0); PG8_BAR; PG8_MMAF(1, 0, At, B0); PG8_MMAF(1, 1, At, B1); PG8_BAR; PG8_SCHED;
.LBB0_878:
	s_ashr_i32 s45, s44, 31
	s_lshl_b64 s[8:9], s[44:45], 17
	s_add_u32 s48, s86, s8
	ds_read_b128 v[2:5], v1
	ds_read_b128 v[6:9], v1 offset:1024
	ds_read_b128 v[10:13], v1 offset:2048
	ds_read_b128 v[14:17], v1 offset:3072
	ds_read_b128 v[18:21], v234
	ds_read_b128 v[22:25], v234 offset:1024
	ds_read_b128 v[26:29], v234 offset:2048
	ds_read_b128 v[30:33], v234 offset:3072
	s_addc_u32 s49, s87, s9
	s_ashr_i32 s43, s42, 31
	s_lshl_b64 s[8:9], s[42:43], 17
	s_add_u32 s50, s70, s8
	s_addc_u32 s51, s71, s9
	s_add_u32 s26, s52, 0x100
	s_addc_u32 s27, s53, 0
	s_add_u32 s60, s54, 0x100
	s_addc_u32 s61, s55, 0
	s_add_u32 s8, s52, 0x180
	s_addc_u32 s9, s53, 0
	ds_read_b128 v[34:37], v235
	ds_read_b128 v[38:41], v235 offset:1024
	ds_read_b128 v[42:45], v235 offset:2048
	ds_read_b128 v[46:49], v235 offset:3072
	ds_read_b128 v[50:53], v235 offset:4096
	ds_read_b128 v[54:57], v235 offset:5120
	ds_read_b128 v[58:61], v235 offset:6144
	ds_read_b128 v[62:65], v235 offset:7168
	s_add_u32 s24, s54, 0x180
	s_addc_u32 s25, s55, 0
	s_add_u32 s62, s52, 0x10080
	s_addc_u32 s63, s53, 0
	s_add_u32 m0, s14, 0xc000
	s_nop 0
	global_load_lds_dwordx4 v230, s[62:63]
	s_nop 0
	s_add_u32 m0, s14, 0xe000
	s_nop 0
	global_load_lds_dwordx4 v232, s[62:63]
	s_waitcnt vmcnt(8)
	s_waitcnt lgkmcnt(0)
	s_barrier
	v_mfma_f32_16x16x32_f16 v[66:69], v[2:5], v[34:37], 0
	s_setprio 1
	v_mfma_f32_16x16x32_f16 v[66:69], v[6:9], v[38:41], v[66:69]
	v_mfma_f32_16x16x32_f16 v[70:73], v[14:17], v[38:41], 0
	v_mfma_f32_16x16x32_f16 v[70:73], v[10:13], v[34:37], v[70:73]
	v_mfma_f32_16x16x32_f16 v[86:89], v[10:13], v[50:53], 0
	v_mfma_f32_16x16x32_f16 v[86:89], v[14:17], v[54:57], v[86:89]
	v_mfma_f32_16x16x32_f16 v[82:85], v[6:9], v[54:57], 0
	v_mfma_f32_16x16x32_f16 v[82:85], v[2:5], v[50:53], v[82:85]
	v_mfma_f32_16x16x32_f16 v[90:93], v[2:5], v[58:61], 0
	v_mfma_f32_16x16x32_f16 v[90:93], v[6:9], v[62:65], v[90:93]
	v_mfma_f32_16x16x32_f16 v[94:97], v[14:17], v[62:65], 0
	v_mfma_f32_16x16x32_f16 v[94:97], v[10:13], v[58:61], v[94:97]
	v_mfma_f32_16x16x32_f16 v[78:81], v[10:13], v[42:45], 0
	v_mfma_f32_16x16x32_f16 v[78:81], v[14:17], v[46:49], v[78:81]
	v_mfma_f32_16x16x32_f16 v[74:77], v[6:9], v[46:49], 0
	v_mfma_f32_16x16x32_f16 v[74:77], v[2:5], v[42:45], v[74:77]
	v_mfma_f32_16x16x32_f16 v[98:101], v[18:21], v[34:37], 0
	v_mfma_f32_16x16x32_f16 v[98:101], v[22:25], v[38:41], v[98:101]
	v_mfma_f32_16x16x32_f16 v[34:37], v[26:29], v[34:37], 0
	v_mfma_f32_16x16x32_f16 v[34:37], v[30:33], v[38:41], v[34:37]
	v_mfma_f32_16x16x32_f16 v[38:41], v[18:21], v[42:45], 0
	v_mfma_f32_16x16x32_f16 v[38:41], v[22:25], v[46:49], v[38:41]
	v_mfma_f32_16x16x32_f16 v[42:45], v[26:29], v[42:45], 0
	v_mfma_f32_16x16x32_f16 v[42:45], v[30:33], v[46:49], v[42:45]
	v_mfma_f32_16x16x32_f16 v[46:49], v[18:21], v[50:53], 0
	v_mfma_f32_16x16x32_f16 v[46:49], v[22:25], v[54:57], v[46:49]
	v_mfma_f32_16x16x32_f16 v[50:53], v[26:29], v[50:53], 0
	v_mfma_f32_16x16x32_f16 v[50:53], v[30:33], v[54:57], v[50:53]
	v_mfma_f32_16x16x32_f16 v[54:57], v[18:21], v[58:61], 0
	v_mfma_f32_16x16x32_f16 v[54:57], v[22:25], v[62:65], v[54:57]
	v_mfma_f32_16x16x32_f16 v[58:61], v[26:29], v[58:61], 0
	v_mfma_f32_16x16x32_f16 v[58:61], v[30:33], v[62:65], v[58:61]
	s_barrier
	s_setprio 0
	ds_read_b128 v[62:65], v235 offset:16384
	ds_read_b128 v[102:105], v235 offset:17408
	ds_read_b128 v[106:109], v235 offset:18432
	ds_read_b128 v[110:113], v235 offset:19456
	ds_read_b128 v[114:117], v235 offset:20480
	ds_read_b128 v[118:121], v235 offset:21504
	ds_read_b128 v[122:125], v235 offset:22528
	ds_read_b128 v[126:129], v235 offset:23552
	s_add_u32 m0, s14, 0x10000
	s_nop 0
	global_load_lds_dwordx4 v231, s[60:61]
	s_nop 0
	s_add_u32 m0, s14, 0x12000
	s_nop 0
	global_load_lds_dwordx4 v233, s[60:61]
	s_add_u32 s60, s54, 0x10100
	s_addc_u32 s61, s55, 0
	s_add_u32 m0, s14, 0x14000
	s_nop 0
	global_load_lds_dwordx4 v231, s[60:61]
	s_nop 0
	s_add_u32 m0, s14, 0x16000
	s_nop 0
	global_load_lds_dwordx4 v233, s[60:61]
	s_nop 0
	s_add_u32 m0, s14, 0
	s_nop 0
	global_load_lds_dwordx4 v230, s[26:27]
	s_nop 0
	s_add_u32 m0, s14, 0x2000
	s_nop 0
	global_load_lds_dwordx4 v232, s[26:27]
	s_waitcnt vmcnt(8)
	s_waitcnt lgkmcnt(0)
	s_barrier
	v_mfma_f32_16x16x32_f16 v[130:133], v[2:5], v[62:65], 0
	s_setprio 1
	v_mfma_f32_16x16x32_f16 v[130:133], v[6:9], v[102:105], v[130:133]
	v_mfma_f32_16x16x32_f16 v[138:141], v[2:5], v[106:109], 0
	v_mfma_f32_16x16x32_f16 v[138:141], v[6:9], v[110:113], v[138:141]
	v_mfma_f32_16x16x32_f16 v[146:149], v[2:5], v[114:117], 0
	v_mfma_f32_16x16x32_f16 v[146:149], v[6:9], v[118:121], v[146:149]
	v_mfma_f32_16x16x32_f16 v[2:5], v[2:5], v[122:125], 0
	v_mfma_f32_16x16x32_f16 v[2:5], v[6:9], v[126:129], v[2:5]
	v_mfma_f32_16x16x32_f16 v[134:137], v[10:13], v[62:65], 0
	v_mfma_f32_16x16x32_f16 v[134:137], v[14:17], v[102:105], v[134:137]
	v_mfma_f32_16x16x32_f16 v[142:145], v[10:13], v[106:109], 0
	v_mfma_f32_16x16x32_f16 v[142:145], v[14:17], v[110:113], v[142:145]
	v_mfma_f32_16x16x32_f16 v[150:153], v[10:13], v[114:117], 0
	v_mfma_f32_16x16x32_f16 v[150:153], v[14:17], v[118:121], v[150:153]
	v_mfma_f32_16x16x32_f16 v[6:9], v[10:13], v[122:125], 0
	v_mfma_f32_16x16x32_f16 v[6:9], v[14:17], v[126:129], v[6:9]
	v_mfma_f32_16x16x32_f16 v[10:13], v[18:21], v[62:65], 0
	v_mfma_f32_16x16x32_f16 v[14:17], v[26:29], v[62:65], 0
	v_mfma_f32_16x16x32_f16 v[10:13], v[22:25], v[102:105], v[10:13]
	v_mfma_f32_16x16x32_f16 v[14:17], v[30:33], v[102:105], v[14:17]
	v_mfma_f32_16x16x32_f16 v[102:105], v[26:29], v[106:109], 0
	v_mfma_f32_16x16x32_f16 v[62:65], v[18:21], v[106:109], 0
	v_mfma_f32_16x16x32_f16 v[154:157], v[30:33], v[110:113], v[102:105]
	v_mfma_f32_16x16x32_f16 v[102:105], v[18:21], v[114:117], 0
	v_mfma_f32_16x16x32_f16 v[18:21], v[18:21], v[122:125], 0
	v_mfma_f32_16x16x32_f16 v[62:65], v[22:25], v[110:113], v[62:65]
	v_mfma_f32_16x16x32_f16 v[158:161], v[22:25], v[118:121], v[102:105]
	v_mfma_f32_16x16x32_f16 v[102:105], v[26:29], v[114:117], 0
	v_mfma_f32_16x16x32_f16 v[18:21], v[22:25], v[126:129], v[18:21]
	v_mfma_f32_16x16x32_f16 v[22:25], v[26:29], v[122:125], 0
	v_mfma_f32_16x16x32_f16 v[162:165], v[30:33], v[118:121], v[102:105]
	v_mfma_f32_16x16x32_f16 v[22:25], v[30:33], v[126:129], v[22:25]
	s_barrier
; #define PG8_STAGE(bufoff, gbase, voff) do { if constexpr (ABL & 1) break; glds16s<(bufoff)>((voff)[0], (const void*)(gbase), ldsbw); glds16s<(bufoff) + 8192>((voff)[1], (const void*)(gbase), ldsbw); } while (0)
; #define PG8_LDA(dst, b, h) do { if constexpr (ABL & 4) break; _Pragma("unroll") for (int m = 0; m < 4; ++m) _Pragma("unroll") for (int k = 0; k < 2; ++k) dst[m][k] = *(const LAS f16x8*)(lds + PG8_SA(b, h) + aoff + m * 2048 + k * 1024); } while (0)
; #define PG8_LDB(dst, b, h) do { if constexpr (ABL & 4) break; _Pragma("unroll") for (int n = 0; n < 2; ++n) _Pragma("unroll") for (int k = 0; k < 2; ++k) dst[n][k] = *(const LAS f16x8*)(lds + PG8_SB(b, h) + boff + n * 2048 + k * 1024); } while (0)
; #define PG8_MMA(ai, bj, At, Bt) do { if constexpr (ABL & 2) break; __builtin_amdgcn_s_setprio(1); _Pragma("unroll") for (int m = 0; m < 4; ++m) _Pragma("unroll") for (int n = 0; n < 2; ++n) _Pragma("unroll") for (int k = 0; k < 2; ++k) \
;         acc[ai][bj][m][n] = __builtin_amdgcn_mfma_f32_16x16x32_f16(Bt[n][k], At[m][k], acc[ai][bj][m][n], 0, 0, 0); __builtin_amdgcn_s_setprio(0); } while (0)
; #define PG8_WAIT_V(n) asm volatile("s_waitcnt vmcnt(" #n ")" ::: "memory")
; #define PG8_WAIT_L(n) asm volatile("s_waitcnt lgkmcnt(" #n ")" ::: "memory")
; #define PG8_BAR __builtin_amdgcn_s_barrier()
; #define PG8_SCHED __builtin_amdgcn_sched_barrier(0)
;     ...
;             PG8_LDB(B0, 1, 0); PG8_LDB(B1, 1, 1); PG8_SCHED; PG8_LDA(At, 1, 0); if (!fin) PG8_STAGE(PG8_SA(0, 1), a2 + hstep, voffA);
;             if (!fin) PG8_WAIT_V(8); else PG8_WAIT_V(0); PG8_WAIT_L(0); PG8_BAR; PG8_MMA(0, 0, At, B0); PG8_MMA(0, 1, At, B1); PG8_BAR; PG8_SCHED;
;             PG8_LDA(At, 1, 1); if (!fin) { PG8_STAGE(PG8_SB(1, 0), b3, voffB); PG8_STAGE(PG8_SB(1, 1), b3 + hstep, voffB); PG8_STAGE(PG8_SA(1, 0), a3, voffA); }
	s_setprio 0
	ds_read_b128 v[26:29], v236
	ds_read_b128 v[30:33], v236 offset:1024
	ds_read_b128 v[102:105], v236 offset:2048
	ds_read_b128 v[106:109], v236 offset:3072
	ds_read_b128 v[166:169], v237
	ds_read_b128 v[170:173], v237 offset:1024
	ds_read_b128 v[174:177], v237 offset:2048
	ds_read_b128 v[178:181], v237 offset:3072
	ds_read_b128 v[110:113], v235 offset:32768
	ds_read_b128 v[114:117], v235 offset:33792
	ds_read_b128 v[118:121], v235 offset:34816
	ds_read_b128 v[122:125], v235 offset:35840
	ds_read_b128 v[126:129], v235 offset:36864
	ds_read_b128 v[182:185], v235 offset:37888
	ds_read_b128 v[186:189], v235 offset:38912
	ds_read_b128 v[190:193], v235 offset:39936
	s_add_u32 s26, s52, 0x10100
	s_addc_u32 s27, s53, 0
	s_add_u32 m0, s14, 0x4000
	s_nop 0
	global_load_lds_dwordx4 v230, s[26:27]
	s_nop 0
	s_add_u32 m0, s14, 0x6000
	s_nop 0
	global_load_lds_dwordx4 v232, s[26:27]
	s_waitcnt vmcnt(8)
	s_waitcnt lgkmcnt(0)
	s_barrier
	v_mfma_f32_16x16x32_f16 v[82:85], v[26:29], v[126:129], v[82:85]
	s_setprio 1
	v_mfma_f32_16x16x32_f16 v[194:197], v[30:33], v[182:185], v[82:85]
	v_mfma_f32_16x16x32_f16 v[82:85], v[102:105], v[126:129], v[86:89]
	v_mfma_f32_16x16x32_f16 v[198:201], v[106:109], v[182:185], v[82:85]
	v_mfma_f32_16x16x32_f16 v[66:69], v[26:29], v[110:113], v[66:69]
	v_mfma_f32_16x16x32_f16 v[66:69], v[30:33], v[114:117], v[66:69]
	v_mfma_f32_16x16x32_f16 v[70:73], v[102:105], v[110:113], v[70:73]
	v_mfma_f32_16x16x32_f16 v[70:73], v[106:109], v[114:117], v[70:73]
	v_mfma_f32_16x16x32_f16 v[82:85], v[26:29], v[186:189], v[90:93]
	v_mfma_f32_16x16x32_f16 v[202:205], v[30:33], v[190:193], v[82:85]
	v_mfma_f32_16x16x32_f16 v[74:77], v[26:29], v[118:121], v[74:77]
	v_mfma_f32_16x16x32_f16 v[74:77], v[30:33], v[122:125], v[74:77]
	v_mfma_f32_16x16x32_f16 v[78:81], v[102:105], v[118:121], v[78:81]
	v_mfma_f32_16x16x32_f16 v[78:81], v[106:109], v[122:125], v[78:81]
	v_mfma_f32_16x16x32_f16 v[82:85], v[102:105], v[186:189], v[94:97]
	v_mfma_f32_16x16x32_f16 v[206:209], v[106:109], v[190:193], v[82:85]
	v_mfma_f32_16x16x32_f16 v[34:37], v[174:177], v[110:113], v[34:37]
	v_mfma_f32_16x16x32_f16 v[214:217], v[178:181], v[114:117], v[34:37]
	v_mfma_f32_16x16x32_f16 v[34:37], v[166:169], v[118:121], v[38:41]
	v_mfma_f32_16x16x32_f16 v[218:221], v[170:173], v[122:125], v[34:37]
	v_mfma_f32_16x16x32_f16 v[34:37], v[174:177], v[118:121], v[42:45]
	v_mfma_f32_16x16x32_f16 v[222:225], v[178:181], v[122:125], v[34:37]
	v_mfma_f32_16x16x32_f16 v[34:37], v[166:169], v[126:129], v[46:49]
	v_mfma_f32_16x16x32_f16 v[238:241], v[170:173], v[182:185], v[34:37]
	v_mfma_f32_16x16x32_f16 v[34:37], v[174:177], v[126:129], v[50:53]
	v_mfma_f32_16x16x32_f16 v[182:185], v[178:181], v[182:185], v[34:37]
	v_mfma_f32_16x16x32_f16 v[34:37], v[166:169], v[186:189], v[54:57]
	v_mfma_f32_16x16x32_f16 v[242:245], v[170:173], v[190:193], v[34:37]
	v_mfma_f32_16x16x32_f16 v[34:37], v[174:177], v[186:189], v[58:61]
	v_mfma_f32_16x16x32_f16 v[186:189], v[178:181], v[190:193], v[34:37]
	v_mfma_f32_16x16x32_f16 v[82:85], v[166:169], v[110:113], v[98:101]
	v_mfma_f32_16x16x32_f16 v[210:213], v[170:173], v[114:117], v[82:85]
	s_barrier
	s_setprio 0
	ds_read_b128 v[42:45], v235 offset:49152
	ds_read_b128 v[46:49], v235 offset:50176
	ds_read_b128 v[50:53], v235 offset:51200
	ds_read_b128 v[54:57], v235 offset:52224
	ds_read_b128 v[58:61], v235 offset:53248
	ds_read_b128 v[126:129], v235 offset:54272
	ds_read_b128 v[190:193], v235 offset:55296
	ds_read_b128 v[246:249], v235 offset:56320
	s_add_u32 m0, s14, 0x18000
	s_nop 0
	global_load_lds_dwordx4 v231, s[24:25]
	s_nop 0
	s_add_u32 m0, s14, 0x1a000
	s_nop 0
	global_load_lds_dwordx4 v233, s[24:25]
	s_add_u32 s24, s54, 0x10180
	s_addc_u32 s25, s55, 0
	s_add_u32 m0, s14, 0x1c000
	s_nop 0
	global_load_lds_dwordx4 v231, s[24:25]
	s_nop 0
	s_add_u32 m0, s14, 0x1e000
	s_nop 0
	global_load_lds_dwordx4 v233, s[24:25]
	s_nop 0
	s_add_u32 m0, s14, 0x8000
	s_nop 0
	global_load_lds_dwordx4 v230, s[8:9]
	s_nop 0
	s_add_u32 m0, s14, 0xa000
	s_nop 0
	global_load_lds_dwordx4 v232, s[8:9]
	s_waitcnt vmcnt(8)
	s_waitcnt lgkmcnt(0)
	s_barrier
; #define PG8_STAGE(bufoff, gbase, voff) do { if constexpr (ABL & 1) break; glds16s<(bufoff)>((voff)[0], (const void*)(gbase), ldsbw); glds16s<(bufoff) + 8192>((voff)[1], (const void*)(gbase), ldsbw); } while (0)
; #define PG8_LDA(dst, b, h) do { if constexpr (ABL & 4) break; _Pragma("unroll") for (int m = 0; m < 4; ++m) _Pragma("unroll") for (int k = 0; k < 2; ++k) dst[m][k] = *(const LAS f16x8*)(lds + PG8_SA(b, h) + aoff + m * 2048 + k * 1024); } while (0)
; #define PG8_LDB(dst, b, h) do { if constexpr (ABL & 4) break; _Pragma("unroll") for (int n = 0; n < 2; ++n) _Pragma("unroll") for (int k = 0; k < 2; ++k) dst[n][k] = *(const LAS f16x8*)(lds + PG8_SB(b, h) + boff + n * 2048 + k * 1024); } while (0)
; #define PG8_MMA(ai, bj, At, Bt) do { if constexpr (ABL & 2) break; __builtin_amdgcn_s_setprio(1); _Pragma("unroll") for (int m = 0; m < 4; ++m) _Pragma("unroll") for (int n = 0; n < 2; ++n) _Pragma("unroll") for (int k = 0; k < 2; ++k) \
;         acc[ai][bj][m][n] = __builtin_amdgcn_mfma_f32_16x16x32_f16(Bt[n][k], At[m][k], acc[ai][bj][m][n], 0, 0, 0); __builtin_amdgcn_s_setprio(0); } while (0)
; #define PG8_WAIT_V(n) asm volatile("s_waitcnt vmcnt(" #n ")" ::: "memory")
;     ...
;             PG8_LDB(B0, 0, 0); PG8_LDB(B1, 0, 1); PG8_SCHED; PG8_LDA(At, 0, 0); PG8_STAGE(PG8_SA(1, 1), a1 + hstep, voffA);
;             PG8_WAIT_V(8); PG8_WAIT_L(0); PG8_BAR; PG8_MMAF(0, 0, At, B0); PG8_MMAF(0, 1, At, B1); PG8_BAR; PG8_SCHED;
;             const bool fin = last && !has_next;
;             PG8_LDA(At, 0, 1); if (!fin) { PG8_STAGE(PG8_SB(0, 0), b2, voffB); PG8_STAGE(PG8_SB(0, 1), b2 + hstep, voffB); PG8_STAGE(PG8_SA(0, 0), a2, voffA); }
;             if (!fin) PG8_WAIT_V(8); else PG8_WAIT_V(2); PG8_WAIT_L(0); PG8_BAR; PG8_MMAF(1, 0, At, B0); PG8_MMAF(1, 1, At, B1); PG8_BAR; PG8_SCHED;
;             PG8_LDB(B0, 1, 0); PG8_LDB(B1, 1, 1); PG8_SCHED; PG8_LDA(At, 1, 0); if (!fin) PG8_STAGE(PG8_SA(0, 1), a2 + hstep, voffA);
;             if (!fin) PG8_WAIT_V(8); else PG8_WAIT_V(0); PG8_WAIT_L(0); PG8_BAR; PG8_MMA(0, 0, At, B0); PG8_MMA(0, 1, At, B1); PG8_BAR; PG8_SCHED;
;             PG8_LDA(At, 1, 1); if (!fin) { PG8_STAGE(PG8_SB(1, 0), b3, voffB); PG8_STAGE(PG8_SB(1, 1), b3 + hstep, voffB); PG8_STAGE(PG8_SA(1, 0), a3, voffA); }
;             if (!fin) PG8_WAIT_V(8); PG8_WAIT_L(0); PG8_BAR; PG8_MMA(1, 0, At, B0); PG8_MMA(1, 1, At, B1); PG8_BAR; PG8_SCHED;
	v_mfma_f32_16x16x32_f16 v[2:5], v[26:29], v[190:193], v[2:5]
	s_setprio 1
	v_mfma_f32_16x16x32_f16 v[98:101], v[30:33], v[246:249], v[2:5]
	v_mfma_f32_16x16x32_f16 v[34:37], v[26:29], v[42:45], v[130:133]
	v_mfma_f32_16x16x32_f16 v[34:37], v[30:33], v[46:49], v[34:37]
	v_mfma_f32_16x16x32_f16 v[38:41], v[102:105], v[42:45], v[134:137]
	v_mfma_f32_16x16x32_f16 v[38:41], v[106:109], v[46:49], v[38:41]
	v_mfma_f32_16x16x32_f16 v[82:85], v[26:29], v[50:53], v[138:141]
	v_mfma_f32_16x16x32_f16 v[82:85], v[30:33], v[54:57], v[82:85]
	v_mfma_f32_16x16x32_f16 v[86:89], v[102:105], v[50:53], v[142:145]
	v_mfma_f32_16x16x32_f16 v[86:89], v[106:109], v[54:57], v[86:89]
	v_mfma_f32_16x16x32_f16 v[90:93], v[26:29], v[58:61], v[146:149]
	v_mfma_f32_16x16x32_f16 v[90:93], v[30:33], v[126:129], v[90:93]
	v_mfma_f32_16x16x32_f16 v[94:97], v[102:105], v[58:61], v[150:153]
	v_mfma_f32_16x16x32_f16 v[94:97], v[106:109], v[126:129], v[94:97]
	v_mfma_f32_16x16x32_f16 v[2:5], v[102:105], v[190:193], v[6:9]
	v_mfma_f32_16x16x32_f16 v[102:105], v[106:109], v[246:249], v[2:5]
	v_mfma_f32_16x16x32_f16 v[2:5], v[166:169], v[42:45], v[10:13]
	v_mfma_f32_16x16x32_f16 v[106:109], v[170:173], v[46:49], v[2:5]
	v_mfma_f32_16x16x32_f16 v[2:5], v[174:177], v[42:45], v[14:17]
	v_mfma_f32_16x16x32_f16 v[110:113], v[178:181], v[46:49], v[2:5]
	v_mfma_f32_16x16x32_f16 v[2:5], v[166:169], v[50:53], v[62:65]
	v_mfma_f32_16x16x32_f16 v[114:117], v[170:173], v[54:57], v[2:5]
	v_mfma_f32_16x16x32_f16 v[2:5], v[174:177], v[50:53], v[154:157]
	v_mfma_f32_16x16x32_f16 v[118:121], v[178:181], v[54:57], v[2:5]
	v_mfma_f32_16x16x32_f16 v[2:5], v[166:169], v[58:61], v[158:161]
	v_mfma_f32_16x16x32_f16 v[122:125], v[170:173], v[126:129], v[2:5]
	v_mfma_f32_16x16x32_f16 v[2:5], v[174:177], v[58:61], v[162:165]
	v_mfma_f32_16x16x32_f16 v[126:129], v[178:181], v[126:129], v[2:5]
	v_mfma_f32_16x16x32_f16 v[2:5], v[166:169], v[190:193], v[18:21]
	v_mfma_f32_16x16x32_f16 v[130:133], v[170:173], v[246:249], v[2:5]
	v_mfma_f32_16x16x32_f16 v[2:5], v[174:177], v[190:193], v[22:25]
	v_mfma_f32_16x16x32_f16 v[134:137], v[178:181], v[246:249], v[2:5]
	s_barrier
	s_setprio 0
	ds_read_b128 v[154:157], v1
	ds_read_b128 v[158:161], v1 offset:1024
	ds_read_b128 v[162:165], v1 offset:2048
	ds_read_b128 v[166:169], v1 offset:3072
	ds_read_b128 v[138:141], v234
	ds_read_b128 v[142:145], v234 offset:1024
	ds_read_b128 v[146:149], v234 offset:2048
	ds_read_b128 v[150:153], v234 offset:3072
	ds_read_b128 v[46:49], v235
	ds_read_b128 v[50:53], v235 offset:1024
	ds_read_b128 v[54:57], v235 offset:2048
	ds_read_b128 v[58:61], v235 offset:3072
	ds_read_b128 v[62:65], v235 offset:4096
	ds_read_b128 v[170:173], v235 offset:5120
	ds_read_b128 v[174:177], v235 offset:6144
	ds_read_b128 v[178:181], v235 offset:7168
	s_add_u32 s8, s52, 0x10180
	s_addc_u32 s9, s53, 0
	s_add_u32 m0, s14, 0xc000
	s_nop 0
	global_load_lds_dwordx4 v230, s[8:9]
	s_nop 0
	s_add_u32 m0, s14, 0xe000
	s_nop 0
	global_load_lds_dwordx4 v232, s[8:9]
	s_waitcnt vmcnt(8)
	s_waitcnt lgkmcnt(0)
	s_barrier
	v_mfma_f32_16x16x32_f16 v[2:5], v[154:157], v[46:49], v[66:69]
	s_setprio 1
	v_mfma_f32_16x16x32_f16 v[2:5], v[158:161], v[50:53], v[2:5]
	v_mfma_f32_16x16x32_f16 v[6:9], v[166:169], v[50:53], v[70:73]
	v_mfma_f32_16x16x32_f16 v[6:9], v[162:165], v[46:49], v[6:9]
	v_mfma_f32_16x16x32_f16 v[14:17], v[162:165], v[54:57], v[78:81]
	v_mfma_f32_16x16x32_f16 v[14:17], v[166:169], v[58:61], v[14:17]
	v_mfma_f32_16x16x32_f16 v[10:13], v[158:161], v[58:61], v[74:77]
	v_mfma_f32_16x16x32_f16 v[10:13], v[154:157], v[54:57], v[10:13]
	v_mfma_f32_16x16x32_f16 v[18:21], v[154:157], v[62:65], v[194:197]
	v_mfma_f32_16x16x32_f16 v[18:21], v[158:161], v[170:173], v[18:21]
	v_mfma_f32_16x16x32_f16 v[22:25], v[166:169], v[170:173], v[198:201]
	v_mfma_f32_16x16x32_f16 v[22:25], v[162:165], v[62:65], v[22:25]
	v_mfma_f32_16x16x32_f16 v[30:33], v[162:165], v[174:177], v[206:209]
	v_mfma_f32_16x16x32_f16 v[30:33], v[166:169], v[178:181], v[30:33]
	v_mfma_f32_16x16x32_f16 v[26:29], v[158:161], v[178:181], v[202:205]
	v_mfma_f32_16x16x32_f16 v[26:29], v[154:157], v[174:177], v[26:29]
	v_mfma_f32_16x16x32_f16 v[66:69], v[138:141], v[174:177], v[242:245]
	v_mfma_f32_16x16x32_f16 v[66:69], v[142:145], v[178:181], v[66:69]
	v_mfma_f32_16x16x32_f16 v[42:45], v[142:145], v[50:53], v[210:213]
	v_mfma_f32_16x16x32_f16 v[42:45], v[138:141], v[46:49], v[42:45]
	v_mfma_f32_16x16x32_f16 v[46:49], v[146:149], v[46:49], v[214:217]
	v_mfma_f32_16x16x32_f16 v[46:49], v[150:153], v[50:53], v[46:49]
	v_mfma_f32_16x16x32_f16 v[70:73], v[150:153], v[178:181], v[186:189]
	v_mfma_f32_16x16x32_f16 v[70:73], v[146:149], v[174:177], v[70:73]
	v_mfma_f32_16x16x32_f16 v[50:53], v[138:141], v[54:57], v[218:221]
	v_mfma_f32_16x16x32_f16 v[50:53], v[142:145], v[58:61], v[50:53]
	v_mfma_f32_16x16x32_f16 v[54:57], v[146:149], v[54:57], v[222:225]
	v_mfma_f32_16x16x32_f16 v[54:57], v[150:153], v[58:61], v[54:57]
	v_mfma_f32_16x16x32_f16 v[58:61], v[138:141], v[62:65], v[238:241]
	v_mfma_f32_16x16x32_f16 v[58:61], v[142:145], v[170:173], v[58:61]
	v_mfma_f32_16x16x32_f16 v[62:65], v[146:149], v[62:65], v[182:185]
	v_mfma_f32_16x16x32_f16 v[62:65], v[150:153], v[170:173], v[62:65]
	s_barrier
	s_setprio 0
	ds_read_b128 v[194:197], v235 offset:16384
	ds_read_b128 v[198:201], v235 offset:17408
	ds_read_b128 v[186:189], v235 offset:18432
	ds_read_b128 v[190:193], v235 offset:19456
	ds_read_b128 v[178:181], v235 offset:20480
	ds_read_b128 v[182:185], v235 offset:21504
	ds_read_b128 v[170:173], v235 offset:22528
	ds_read_b128 v[174:177], v235 offset:23552
	s_mov_b64 s[8:9], -1
	s_and_b64 vcc, exec, s[4:5]
	s_cbranch_vccz .LBB0_880
	s_waitcnt vmcnt(2)
	s_mov_b64 s[8:9], 0

; #define PG8_STAGE(bufoff, gbase, voff) do { if constexpr (ABL & 1) break; glds16s<(bufoff)>((voff)[0], (const void*)(gbase), ldsbw); glds16s<(bufoff) + 8192>((voff)[1], (const void*)(gbase), ldsbw); } while (0)
; #define PG8_LDA(dst, b, h) do { if constexpr (ABL & 4) break; _Pragma("unroll") for (int m = 0; m < 4; ++m) _Pragma("unroll") for (int k = 0; k < 2; ++k) dst[m][k] = *(const LAS f16x8*)(lds + PG8_SA(b, h) + aoff + m * 2048 + k * 1024); } while (0)
; #define PG8_LDB(dst, b, h) do { if constexpr (ABL & 4) break; _Pragma("unroll") for (int n = 0; n < 2; ++n) _Pragma("unroll") for (int k = 0; k < 2; ++k) dst[n][k] = *(const LAS f16x8*)(lds + PG8_SB(b, h) + boff + n * 2048 + k * 1024); } while (0)
; #define PG8_MMA(ai, bj, At, Bt) do { if constexpr (ABL & 2) break; __builtin_amdgcn_s_setprio(1); _Pragma("unroll") for (int m = 0; m < 4; ++m) _Pragma("unroll") for (int n = 0; n < 2; ++n) _Pragma("unroll") for (int k = 0; k < 2; ++k) \
;         acc[ai][bj][m][n] = __builtin_amdgcn_mfma_f32_16x16x32_f16(Bt[n][k], At[m][k], acc[ai][bj][m][n], 0, 0, 0); __builtin_amdgcn_s_setprio(0); } while (0)
; #define PG8_MMAF(ai, bj, At, Bt) do { if (t == 0) PG8_MMA0(ai, bj, At, Bt); else PG8_MMA(ai, bj, At, Bt); } while (0)
; #define PG8_WAIT_V(n) asm volatile("s_waitcnt vmcnt(" #n ")" ::: "memory")
; #define PG8_WAIT_L(n) asm volatile("s_waitcnt lgkmcnt(" #n ")" ::: "memory")
; #define PG8_BAR __builtin_amdgcn_s_barrier()
; #define PG8_SCHED __builtin_amdgcn_sched_barrier(0)
;     ...
;             if (!fin) PG8_WAIT_V(8); else PG8_WAIT_V(2); PG8_WAIT_L(0); PG8_BAR; PG8_MMAF(1, 0, At, B0); PG8_MMAF(1, 1, At, B1); PG8_BAR; PG8_SCHED;
;             PG8_LDB(B0, 1, 0); PG8_LDB(B1, 1, 1); PG8_SCHED; PG8_LDA(At, 1, 0); if (!fin) PG8_STAGE(PG8_SA(0, 1), a2 + hstep, voffA);
;             if (!fin) PG8_WAIT_V(8); else PG8_WAIT_V(0); PG8_WAIT_L(0); PG8_BAR; PG8_MMA(0, 0, At, B0); PG8_MMA(0, 1, At, B1); PG8_BAR; PG8_SCHED;
;             PG8_LDA(At, 1, 1); if (!fin) { PG8_STAGE(PG8_SB(1, 0), b3, voffB); PG8_STAGE(PG8_SB(1, 1), b3 + hstep, voffB); PG8_STAGE(PG8_SA(1, 0), a3, voffA); }
;             if (!fin) PG8_WAIT_V(8); PG8_WAIT_L(0); PG8_BAR; PG8_MMA(1, 0, At, B0); PG8_MMA(1, 1, At, B1); PG8_BAR; PG8_SCHED;
.LBB0_888:
	s_waitcnt lgkmcnt(0)
	s_barrier
	v_mfma_f32_16x16x32_f16 v[10:13], v[170:173], v[218:221], v[74:77]
	s_setprio 1
	v_mfma_f32_16x16x32_f16 v[194:197], v[174:177], v[222:225], v[10:13]
	v_mfma_f32_16x16x32_f16 v[10:13], v[182:185], v[222:225], v[78:81]
	v_mfma_f32_16x16x32_f16 v[198:201], v[178:181], v[218:221], v[10:13]
	v_mfma_f32_16x16x32_f16 v[14:17], v[178:181], v[30:33], v[102:105]
	v_mfma_f32_16x16x32_f16 v[14:17], v[182:185], v[210:213], v[14:17]
	v_mfma_f32_16x16x32_f16 v[10:13], v[170:173], v[58:61], v[82:85]
	v_mfma_f32_16x16x32_f16 v[66:69], v[174:177], v[214:217], v[10:13]
	v_mfma_f32_16x16x32_f16 v[10:13], v[182:185], v[214:217], v[86:89]
	v_mfma_f32_16x16x32_f16 v[70:73], v[178:181], v[58:61], v[10:13]
	v_mfma_f32_16x16x32_f16 v[10:13], v[170:173], v[26:29], v[90:93]
	v_mfma_f32_16x16x32_f16 v[42:45], v[174:177], v[62:65], v[10:13]
	v_mfma_f32_16x16x32_f16 v[10:13], v[182:185], v[62:65], v[94:97]
	v_mfma_f32_16x16x32_f16 v[46:49], v[178:181], v[26:29], v[10:13]
	v_mfma_f32_16x16x32_f16 v[10:13], v[170:173], v[30:33], v[98:101]
	v_mfma_f32_16x16x32_f16 v[10:13], v[174:177], v[210:213], v[10:13]
	v_mfma_f32_16x16x32_f16 v[74:77], v[146:149], v[218:221], v[106:109]
	v_mfma_f32_16x16x32_f16 v[82:85], v[150:153], v[222:225], v[74:77]
	v_mfma_f32_16x16x32_f16 v[74:77], v[158:161], v[222:225], v[110:113]
	v_mfma_f32_16x16x32_f16 v[86:89], v[154:157], v[218:221], v[74:77]
	v_mfma_f32_16x16x32_f16 v[74:77], v[146:149], v[58:61], v[114:117]
	v_mfma_f32_16x16x32_f16 v[74:77], v[150:153], v[214:217], v[74:77]
	v_mfma_f32_16x16x32_f16 v[58:61], v[154:157], v[58:61], v[118:121]
	v_mfma_f32_16x16x32_f16 v[78:81], v[158:161], v[214:217], v[58:61]
	v_mfma_f32_16x16x32_f16 v[58:61], v[146:149], v[26:29], v[122:125]
	v_mfma_f32_16x16x32_f16 v[58:61], v[150:153], v[62:65], v[58:61]
	v_mfma_f32_16x16x32_f16 v[26:29], v[154:157], v[26:29], v[126:129]
	v_mfma_f32_16x16x32_f16 v[62:65], v[158:161], v[62:65], v[26:29]
	v_mfma_f32_16x16x32_f16 v[26:29], v[146:149], v[30:33], v[130:133]
	v_mfma_f32_16x16x32_f16 v[26:29], v[150:153], v[210:213], v[26:29]
	v_mfma_f32_16x16x32_f16 v[30:33], v[154:157], v[30:33], v[134:137]
	v_mfma_f32_16x16x32_f16 v[30:33], v[158:161], v[210:213], v[30:33]
	s_barrier
	s_setprio 0
	s_andn2_b64 vcc, exec, s[6:7]
	s_cbranch_vccnz .LBB0_890
	s_barrier

; #define PG8_STAGE(bufoff, gbase, voff) do { if constexpr (ABL & 1) break; glds16s<(bufoff)>((voff)[0], (const void*)(gbase), ldsbw); glds16s<(bufoff) + 8192>((voff)[1], (const void*)(gbase), ldsbw); } while (0)
; #define PG8_LDA(dst, b, h) do { if constexpr (ABL & 4) break; _Pragma("unroll") for (int m = 0; m < 4; ++m) _Pragma("unroll") for (int k = 0; k < 2; ++k) dst[m][k] = *(const LAS f16x8*)(lds + PG8_SA(b, h) + aoff + m * 2048 + k * 1024); } while (0)
; #define PG8_LDB(dst, b, h) do { if constexpr (ABL & 4) break; _Pragma("unroll") for (int n = 0; n < 2; ++n) _Pragma("unroll") for (int k = 0; k < 2; ++k) dst[n][k] = *(const LAS f16x8*)(lds + PG8_SB(b, h) + boff + n * 2048 + k * 1024); } while (0)
; #define PG8_MMAF(ai, bj, At, Bt) do { if (t == 0) PG8_MMA0(ai, bj, At, Bt); else PG8_MMA(ai, bj, At, Bt); } while (0)
; #define PG8_WAIT_V(n) asm volatile("s_waitcnt vmcnt(" #n ")" ::: "memory")
; #define PG8_WAIT_L(n) asm volatile("s_waitcnt lgkmcnt(" #n ")" ::: "memory")
; #define PG8_BAR __builtin_amdgcn_s_barrier()
; #define PG8_SCHED __builtin_amdgcn_sched_barrier(0)
;     ...
;             PG8_LDB(B0, 0, 0); PG8_LDB(B1, 0, 1); PG8_SCHED; PG8_LDA(At, 0, 0); PG8_STAGE(PG8_SA(1, 1), a1 + hstep, voffA);
;             PG8_WAIT_V(8); PG8_WAIT_L(0); PG8_BAR; PG8_MMAF(0, 0, At, B0); PG8_MMAF(0, 1, At, B1); PG8_BAR; PG8_SCHED;
;             const bool fin = last && !has_next;
;             PG8_LDA(At, 0, 1); if (!fin) { PG8_STAGE(PG8_SB(0, 0), b2, voffB); PG8_STAGE(PG8_SB(0, 1), b2 + hstep, voffB); PG8_STAGE(PG8_SA(0, 0), a2, voffA); }
;             if (!fin) PG8_WAIT_V(8); else PG8_WAIT_V(2); PG8_WAIT_L(0); PG8_BAR; PG8_MMAF(1, 0, At, B0); PG8_MMAF(1, 1, At, B1); PG8_BAR; PG8_SCHED;
.LBB0_987:
	s_waitcnt lgkmcnt(0)
	ds_read_b128 v[2:5], v213
	ds_read_b128 v[6:9], v213 offset:1024
	ds_read_b128 v[10:13], v213 offset:2048
	ds_read_b128 v[14:17], v213 offset:3072
	ds_read_b128 v[18:21], v214
	ds_read_b128 v[22:25], v214 offset:1024
	ds_read_b128 v[26:29], v214 offset:2048
	ds_read_b128 v[30:33], v214 offset:3072
	s_add_u32 s50, s54, 0x100
	s_addc_u32 s51, s55, 0
	s_add_u32 s24, s52, 0x100
	s_addc_u32 s25, s53, 0
	s_add_u32 s6, s54, 0x180
	s_addc_u32 s7, s55, 0
	ds_read_b128 v[34:37], v215
	ds_read_b128 v[38:41], v215 offset:1024
	ds_read_b128 v[42:45], v215 offset:2048
	ds_read_b128 v[46:49], v215 offset:3072
	ds_read_b128 v[50:53], v215 offset:4096
	ds_read_b128 v[54:57], v215 offset:5120
	ds_read_b128 v[58:61], v215 offset:6144
	ds_read_b128 v[62:65], v215 offset:7168
	s_add_u32 s8, s52, 0x180
	s_addc_u32 s9, s53, 0
	s_add_u32 s26, s54, 0xb0080
	s_addc_u32 s27, s55, 0
	s_add_u32 m0, s28, 0xc000
	s_nop 0
	global_load_lds_dwordx4 v1, s[26:27]
	s_nop 0
	s_add_u32 m0, s28, 0xe000
	s_nop 0
	global_load_lds_dwordx4 v211, s[26:27]
	s_waitcnt vmcnt(8)
	s_waitcnt lgkmcnt(0)
	s_barrier
	v_mfma_f32_16x16x32_f16 v[70:73], v[10:13], v[34:37], 0
	s_setprio 1
	v_mfma_f32_16x16x32_f16 v[70:73], v[14:17], v[38:41], v[70:73]
	v_mfma_f32_16x16x32_f16 v[86:89], v[14:17], v[54:57], 0
	v_mfma_f32_16x16x32_f16 v[86:89], v[10:13], v[50:53], v[86:89]
	v_mfma_f32_16x16x32_f16 v[82:85], v[2:5], v[50:53], 0
	v_mfma_f32_16x16x32_f16 v[82:85], v[6:9], v[54:57], v[82:85]
	v_mfma_f32_16x16x32_f16 v[74:77], v[6:9], v[46:49], 0
	v_mfma_f32_16x16x32_f16 v[74:77], v[2:5], v[42:45], v[74:77]
	v_mfma_f32_16x16x32_f16 v[66:69], v[2:5], v[34:37], 0
	v_mfma_f32_16x16x32_f16 v[66:69], v[6:9], v[38:41], v[66:69]
	v_mfma_f32_16x16x32_f16 v[90:93], v[6:9], v[62:65], 0
	v_mfma_f32_16x16x32_f16 v[90:93], v[2:5], v[58:61], v[90:93]
	v_mfma_f32_16x16x32_f16 v[94:97], v[10:13], v[58:61], 0
	v_mfma_f32_16x16x32_f16 v[94:97], v[14:17], v[62:65], v[94:97]
	v_mfma_f32_16x16x32_f16 v[78:81], v[14:17], v[46:49], 0
	v_mfma_f32_16x16x32_f16 v[78:81], v[10:13], v[42:45], v[78:81]
	v_mfma_f32_16x16x32_f16 v[98:101], v[18:21], v[34:37], 0
	v_mfma_f32_16x16x32_f16 v[98:101], v[22:25], v[38:41], v[98:101]
	v_mfma_f32_16x16x32_f16 v[34:37], v[26:29], v[34:37], 0
	v_mfma_f32_16x16x32_f16 v[34:37], v[30:33], v[38:41], v[34:37]
	v_mfma_f32_16x16x32_f16 v[38:41], v[18:21], v[42:45], 0
	v_mfma_f32_16x16x32_f16 v[38:41], v[22:25], v[46:49], v[38:41]
	v_mfma_f32_16x16x32_f16 v[42:45], v[26:29], v[42:45], 0
	v_mfma_f32_16x16x32_f16 v[42:45], v[30:33], v[46:49], v[42:45]
	v_mfma_f32_16x16x32_f16 v[46:49], v[18:21], v[50:53], 0
	v_mfma_f32_16x16x32_f16 v[46:49], v[22:25], v[54:57], v[46:49]
	v_mfma_f32_16x16x32_f16 v[50:53], v[26:29], v[50:53], 0
	v_mfma_f32_16x16x32_f16 v[50:53], v[30:33], v[54:57], v[50:53]
	v_mfma_f32_16x16x32_f16 v[54:57], v[18:21], v[58:61], 0
	v_mfma_f32_16x16x32_f16 v[54:57], v[22:25], v[62:65], v[54:57]
	v_mfma_f32_16x16x32_f16 v[58:61], v[26:29], v[58:61], 0
	v_mfma_f32_16x16x32_f16 v[58:61], v[30:33], v[62:65], v[58:61]
	s_barrier
	s_setprio 0
	ds_read_b128 v[62:65], v215 offset:16384
	ds_read_b128 v[102:105], v215 offset:17408
	ds_read_b128 v[106:109], v215 offset:18432
	ds_read_b128 v[110:113], v215 offset:19456
	ds_read_b128 v[114:117], v215 offset:20480
	ds_read_b128 v[118:121], v215 offset:21504
	ds_read_b128 v[122:125], v215 offset:22528
	ds_read_b128 v[126:129], v215 offset:23552
	s_add_u32 m0, s28, 0x10000
	s_nop 0
	global_load_lds_dwordx4 v210, s[24:25]
	s_nop 0
	s_add_u32 m0, s28, 0x12000
	s_nop 0
	global_load_lds_dwordx4 v212, s[24:25]
	s_add_u32 s24, s52, 0xb0100
	s_addc_u32 s25, s53, 0
	s_add_u32 m0, s28, 0x14000
	s_nop 0
	global_load_lds_dwordx4 v210, s[24:25]
	s_nop 0
	s_add_u32 m0, s28, 0x16000
	s_nop 0
	global_load_lds_dwordx4 v212, s[24:25]
	s_nop 0
	s_add_u32 m0, s28, 0
	s_nop 0
	global_load_lds_dwordx4 v1, s[50:51]
	s_nop 0
	s_add_u32 m0, s28, 0x2000
	s_nop 0
	global_load_lds_dwordx4 v211, s[50:51]
	s_waitcnt vmcnt(8)
	s_waitcnt lgkmcnt(0)
	s_barrier
	v_mfma_f32_16x16x32_f16 v[130:133], v[2:5], v[62:65], 0
	s_setprio 1
	v_mfma_f32_16x16x32_f16 v[138:141], v[6:9], v[102:105], v[130:133]
	v_mfma_f32_16x16x32_f16 v[130:133], v[10:13], v[62:65], 0
	v_mfma_f32_16x16x32_f16 v[158:161], v[14:17], v[102:105], v[130:133]
	v_mfma_f32_16x16x32_f16 v[130:133], v[2:5], v[106:109], 0
	v_mfma_f32_16x16x32_f16 v[162:165], v[6:9], v[110:113], v[130:133]
	v_mfma_f32_16x16x32_f16 v[130:133], v[10:13], v[106:109], 0
	v_mfma_f32_16x16x32_f16 v[166:169], v[14:17], v[110:113], v[130:133]
	v_mfma_f32_16x16x32_f16 v[130:133], v[2:5], v[114:117], 0
	v_mfma_f32_16x16x32_f16 v[170:173], v[6:9], v[118:121], v[130:133]
	v_mfma_f32_16x16x32_f16 v[2:5], v[2:5], v[122:125], 0
	v_mfma_f32_16x16x32_f16 v[2:5], v[6:9], v[126:129], v[2:5]
	v_mfma_f32_16x16x32_f16 v[6:9], v[10:13], v[122:125], 0
	v_mfma_f32_16x16x32_f16 v[6:9], v[14:17], v[126:129], v[6:9]
	v_mfma_f32_16x16x32_f16 v[130:133], v[10:13], v[114:117], 0
	v_mfma_f32_16x16x32_f16 v[174:177], v[14:17], v[118:121], v[130:133]
	v_mfma_f32_16x16x32_f16 v[10:13], v[18:21], v[62:65], 0
	v_mfma_f32_16x16x32_f16 v[178:181], v[22:25], v[102:105], v[10:13]
	v_mfma_f32_16x16x32_f16 v[10:13], v[26:29], v[62:65], 0
	v_mfma_f32_16x16x32_f16 v[102:105], v[30:33], v[102:105], v[10:13]
	v_mfma_f32_16x16x32_f16 v[10:13], v[18:21], v[106:109], 0
	v_mfma_f32_16x16x32_f16 v[182:185], v[22:25], v[110:113], v[10:13]
	v_mfma_f32_16x16x32_f16 v[10:13], v[26:29], v[106:109], 0
	v_mfma_f32_16x16x32_f16 v[186:189], v[30:33], v[110:113], v[10:13]
	v_mfma_f32_16x16x32_f16 v[10:13], v[18:21], v[114:117], 0
	v_mfma_f32_16x16x32_f16 v[190:193], v[22:25], v[118:121], v[10:13]
	v_mfma_f32_16x16x32_f16 v[10:13], v[26:29], v[114:117], 0
	v_mfma_f32_16x16x32_f16 v[114:117], v[30:33], v[118:121], v[10:13]
	v_mfma_f32_16x16x32_f16 v[10:13], v[18:21], v[122:125], 0
	v_mfma_f32_16x16x32_f16 v[194:197], v[22:25], v[126:129], v[10:13]
	v_mfma_f32_16x16x32_f16 v[10:13], v[26:29], v[122:125], 0
	v_mfma_f32_16x16x32_f16 v[126:129], v[30:33], v[126:129], v[10:13]
	s_barrier
; #define PG8_STAGE(bufoff, gbase, voff) do { if constexpr (ABL & 1) break; glds16s<(bufoff)>((voff)[0], (const void*)(gbase), ldsbw); glds16s<(bufoff) + 8192>((voff)[1], (const void*)(gbase), ldsbw); } while (0)
; #define PG8_LDA(dst, b, h) do { if constexpr (ABL & 4) break; _Pragma("unroll") for (int m = 0; m < 4; ++m) _Pragma("unroll") for (int k = 0; k < 2; ++k) dst[m][k] = *(const LAS f16x8*)(lds + PG8_SA(b, h) + aoff + m * 2048 + k * 1024); } while (0)
; #define PG8_LDB(dst, b, h) do { if constexpr (ABL & 4) break; _Pragma("unroll") for (int n = 0; n < 2; ++n) _Pragma("unroll") for (int k = 0; k < 2; ++k) dst[n][k] = *(const LAS f16x8*)(lds + PG8_SB(b, h) + boff + n * 2048 + k * 1024); } while (0)
; #define PG8_MMA(ai, bj, At, Bt) do { if constexpr (ABL & 2) break; __builtin_amdgcn_s_setprio(1); _Pragma("unroll") for (int m = 0; m < 4; ++m) _Pragma("unroll") for (int n = 0; n < 2; ++n) _Pragma("unroll") for (int k = 0; k < 2; ++k) \
;         acc[ai][bj][m][n] = __builtin_amdgcn_mfma_f32_16x16x32_f16(Bt[n][k], At[m][k], acc[ai][bj][m][n], 0, 0, 0); __builtin_amdgcn_s_setprio(0); } while (0)
; #define PG8_WAIT_V(n) asm volatile("s_waitcnt vmcnt(" #n ")" ::: "memory")
; #define PG8_WAIT_L(n) asm volatile("s_waitcnt lgkmcnt(" #n ")" ::: "memory")
; #define PG8_BAR __builtin_amdgcn_s_barrier()
; #define PG8_SCHED __builtin_amdgcn_sched_barrier(0)
;     ...
;             PG8_LDB(B0, 1, 0); PG8_LDB(B1, 1, 1); PG8_SCHED; PG8_LDA(At, 1, 0); if (!fin) PG8_STAGE(PG8_SA(0, 1), a2 + hstep, voffA);
;             if (!fin) PG8_WAIT_V(8); else PG8_WAIT_V(0); PG8_WAIT_L(0); PG8_BAR; PG8_MMA(0, 0, At, B0); PG8_MMA(0, 1, At, B1); PG8_BAR; PG8_SCHED;
;             PG8_LDA(At, 1, 1); if (!fin) { PG8_STAGE(PG8_SB(1, 0), b3, voffB); PG8_STAGE(PG8_SB(1, 1), b3 + hstep, voffB); PG8_STAGE(PG8_SA(1, 0), a3, voffA); }
;             if (!fin) PG8_WAIT_V(8); PG8_WAIT_L(0); PG8_BAR; PG8_MMA(1, 0, At, B0); PG8_MMA(1, 1, At, B1); PG8_BAR; PG8_SCHED;
	s_setprio 0
	s_nop 4
	ds_read_b128 v[10:13], v216
	ds_read_b128 v[14:17], v216 offset:1024
	ds_read_b128 v[18:21], v216 offset:2048
	ds_read_b128 v[22:25], v216 offset:3072
	ds_read_b128 v[198:201], v217
	ds_read_b128 v[202:205], v217 offset:1024
	ds_read_b128 v[220:223], v217 offset:2048
	ds_read_b128 v[224:227], v217 offset:3072
	ds_read_b128 v[26:29], v215 offset:32768
	ds_read_b128 v[30:33], v215 offset:33792
	ds_read_b128 v[62:65], v215 offset:34816
	ds_read_b128 v[118:121], v215 offset:35840
	ds_read_b128 v[228:231], v215 offset:36864
	ds_read_b128 v[232:235], v215 offset:37888
	ds_read_b128 v[236:239], v215 offset:38912
	ds_read_b128 v[240:243], v215 offset:39936
	s_add_u32 s24, s54, 0xb0100
	s_addc_u32 s25, s55, 0
	s_add_u32 m0, s28, 0x4000
	s_nop 0
	global_load_lds_dwordx4 v1, s[24:25]
	s_nop 0
	s_add_u32 m0, s28, 0x6000
	s_nop 0
	global_load_lds_dwordx4 v211, s[24:25]
	s_waitcnt vmcnt(8)
	s_waitcnt lgkmcnt(0)
	s_barrier
	v_mfma_f32_16x16x32_f16 v[66:69], v[10:13], v[26:29], v[66:69]
	s_setprio 1
	v_mfma_f32_16x16x32_f16 v[154:157], v[14:17], v[30:33], v[66:69]
	v_mfma_f32_16x16x32_f16 v[66:69], v[18:21], v[26:29], v[70:73]
	v_mfma_f32_16x16x32_f16 v[150:153], v[22:25], v[30:33], v[66:69]
	v_mfma_f32_16x16x32_f16 v[66:69], v[10:13], v[62:65], v[74:77]
	v_mfma_f32_16x16x32_f16 v[134:137], v[14:17], v[118:121], v[66:69]
	v_mfma_f32_16x16x32_f16 v[66:69], v[18:21], v[62:65], v[78:81]
	v_mfma_f32_16x16x32_f16 v[130:133], v[22:25], v[118:121], v[66:69]
	v_mfma_f32_16x16x32_f16 v[66:69], v[10:13], v[228:231], v[82:85]
	v_mfma_f32_16x16x32_f16 v[110:113], v[14:17], v[232:235], v[66:69]
	v_mfma_f32_16x16x32_f16 v[66:69], v[18:21], v[228:231], v[86:89]
	v_mfma_f32_16x16x32_f16 v[106:109], v[22:25], v[232:235], v[66:69]
	v_mfma_f32_16x16x32_f16 v[66:69], v[10:13], v[236:239], v[90:93]
	v_mfma_f32_16x16x32_f16 v[86:89], v[14:17], v[240:243], v[66:69]
	v_mfma_f32_16x16x32_f16 v[66:69], v[18:21], v[236:239], v[94:97]
	v_mfma_f32_16x16x32_f16 v[82:85], v[22:25], v[240:243], v[66:69]
	v_mfma_f32_16x16x32_f16 v[66:69], v[198:201], v[26:29], v[98:101]
	v_mfma_f32_16x16x32_f16 v[146:149], v[202:205], v[30:33], v[66:69]
	v_mfma_f32_16x16x32_f16 v[26:29], v[220:223], v[26:29], v[34:37]
	v_mfma_f32_16x16x32_f16 v[142:145], v[224:227], v[30:33], v[26:29]
	v_mfma_f32_16x16x32_f16 v[26:29], v[198:201], v[62:65], v[38:41]
	v_mfma_f32_16x16x32_f16 v[122:125], v[202:205], v[118:121], v[26:29]
	v_mfma_f32_16x16x32_f16 v[26:29], v[220:223], v[62:65], v[42:45]
	v_mfma_f32_16x16x32_f16 v[118:121], v[224:227], v[118:121], v[26:29]
	v_mfma_f32_16x16x32_f16 v[26:29], v[198:201], v[228:231], v[46:49]
	v_mfma_f32_16x16x32_f16 v[98:101], v[202:205], v[232:235], v[26:29]
	v_mfma_f32_16x16x32_f16 v[26:29], v[220:223], v[228:231], v[50:53]
	v_mfma_f32_16x16x32_f16 v[94:97], v[224:227], v[232:235], v[26:29]
	v_mfma_f32_16x16x32_f16 v[26:29], v[198:201], v[236:239], v[54:57]
	v_mfma_f32_16x16x32_f16 v[74:77], v[202:205], v[240:243], v[26:29]
	v_mfma_f32_16x16x32_f16 v[26:29], v[220:223], v[236:239], v[58:61]
	v_mfma_f32_16x16x32_f16 v[70:73], v[224:227], v[240:243], v[26:29]
	s_barrier
	s_setprio 0
	ds_read_b128 v[34:37], v215 offset:49152
	ds_read_b128 v[38:41], v215 offset:50176
	ds_read_b128 v[66:69], v215 offset:51200
	ds_read_b128 v[78:81], v215 offset:52224
	ds_read_b128 v[90:93], v215 offset:53248
	ds_read_b128 v[228:231], v215 offset:54272
	ds_read_b128 v[232:235], v215 offset:55296
	ds_read_b128 v[236:239], v215 offset:56320
	s_add_u32 m0, s28, 0x18000
	s_nop 0
	global_load_lds_dwordx4 v210, s[8:9]
	s_nop 0
	s_add_u32 m0, s28, 0x1a000
	s_nop 0
	global_load_lds_dwordx4 v212, s[8:9]
	s_add_u32 s8, s52, 0xb0180
	s_addc_u32 s9, s53, 0
	s_add_u32 m0, s28, 0x1c000
	s_nop 0
	global_load_lds_dwordx4 v210, s[8:9]
	s_nop 0
	s_add_u32 m0, s28, 0x1e000
	s_nop 0
	global_load_lds_dwordx4 v212, s[8:9]
	s_nop 0
	s_add_u32 m0, s28, 0x8000
	s_nop 0
	global_load_lds_dwordx4 v1, s[6:7]
	s_nop 0
	s_add_u32 m0, s28, 0xa000
	s_nop 0
	global_load_lds_dwordx4 v211, s[6:7]
	s_waitcnt vmcnt(8)
	s_waitcnt lgkmcnt(0)
	s_barrier
	v_mfma_f32_16x16x32_f16 v[26:29], v[10:13], v[34:37], v[138:141]
	s_setprio 1
	v_mfma_f32_16x16x32_f16 v[62:65], v[14:17], v[38:41], v[26:29]
	v_mfma_f32_16x16x32_f16 v[26:29], v[22:25], v[38:41], v[158:161]
	v_mfma_f32_16x16x32_f16 v[58:61], v[18:21], v[34:37], v[26:29]
	v_mfma_f32_16x16x32_f16 v[26:29], v[10:13], v[66:69], v[162:165]
	v_mfma_f32_16x16x32_f16 v[46:49], v[14:17], v[78:81], v[26:29]
	v_mfma_f32_16x16x32_f16 v[26:29], v[22:25], v[78:81], v[166:169]
	v_mfma_f32_16x16x32_f16 v[42:45], v[18:21], v[66:69], v[26:29]
	v_mfma_f32_16x16x32_f16 v[26:29], v[10:13], v[90:93], v[170:173]
	v_mfma_f32_16x16x32_f16 v[30:33], v[14:17], v[228:231], v[26:29]
	v_mfma_f32_16x16x32_f16 v[26:29], v[22:25], v[228:231], v[174:177]
	v_mfma_f32_16x16x32_f16 v[26:29], v[18:21], v[90:93], v[26:29]
	v_mfma_f32_16x16x32_f16 v[2:5], v[10:13], v[232:235], v[2:5]
	v_mfma_f32_16x16x32_f16 v[14:17], v[14:17], v[236:239], v[2:5]
	v_mfma_f32_16x16x32_f16 v[2:5], v[22:25], v[236:239], v[6:9]
	v_mfma_f32_16x16x32_f16 v[10:13], v[18:21], v[232:235], v[2:5]
	v_mfma_f32_16x16x32_f16 v[2:5], v[198:201], v[34:37], v[178:181]
	v_mfma_f32_16x16x32_f16 v[54:57], v[202:205], v[38:41], v[2:5]
	v_mfma_f32_16x16x32_f16 v[2:5], v[224:227], v[38:41], v[102:105]
	v_mfma_f32_16x16x32_f16 v[50:53], v[220:223], v[34:37], v[2:5]
	v_mfma_f32_16x16x32_f16 v[2:5], v[198:201], v[66:69], v[182:185]
	v_mfma_f32_16x16x32_f16 v[38:41], v[202:205], v[78:81], v[2:5]
	v_mfma_f32_16x16x32_f16 v[2:5], v[224:227], v[78:81], v[186:189]
	v_mfma_f32_16x16x32_f16 v[34:37], v[220:223], v[66:69], v[2:5]
	v_mfma_f32_16x16x32_f16 v[2:5], v[198:201], v[90:93], v[190:193]
	v_mfma_f32_16x16x32_f16 v[22:25], v[202:205], v[228:231], v[2:5]
	v_mfma_f32_16x16x32_f16 v[2:5], v[224:227], v[228:231], v[114:117]
	v_mfma_f32_16x16x32_f16 v[18:21], v[220:223], v[90:93], v[2:5]
	v_mfma_f32_16x16x32_f16 v[2:5], v[198:201], v[232:235], v[194:197]
	v_mfma_f32_16x16x32_f16 v[6:9], v[202:205], v[236:239], v[2:5]
	v_mfma_f32_16x16x32_f16 v[2:5], v[224:227], v[236:239], v[126:129]
	v_mfma_f32_16x16x32_f16 v[2:5], v[220:223], v[232:235], v[2:5]
	s_barrier
	s_setprio 0
	s_add_u32 s52, s52, 0x200
	s_addc_u32 s53, s53, 0
	s_mov_b32 s54, 0
	s_branch .LBB0_989

; #define PG8_STAGE(bufoff, gbase, voff) do { if constexpr (ABL & 1) break; glds16s<(bufoff)>((voff)[0], (const void*)(gbase), ldsbw); glds16s<(bufoff) + 8192>((voff)[1], (const void*)(gbase), ldsbw); } while (0)
; #define PG8_LDA(dst, b, h) do { if constexpr (ABL & 4) break; _Pragma("unroll") for (int m = 0; m < 4; ++m) _Pragma("unroll") for (int k = 0; k < 2; ++k) dst[m][k] = *(const LAS f16x8*)(lds + PG8_SA(b, h) + aoff + m * 2048 + k * 1024); } while (0)
; #define PG8_LDB(dst, b, h) do { if constexpr (ABL & 4) break; _Pragma("unroll") for (int n = 0; n < 2; ++n) _Pragma("unroll") for (int k = 0; k < 2; ++k) dst[n][k] = *(const LAS f16x8*)(lds + PG8_SB(b, h) + boff + n * 2048 + k * 1024); } while (0)
; #define PG8_MMAF(ai, bj, At, Bt) do { if (t == 0) PG8_MMA0(ai, bj, At, Bt); else PG8_MMA(ai, bj, At, Bt); } while (0)
; #define PG8_WAIT_V(n) asm volatile("s_waitcnt vmcnt(" #n ")" ::: "memory")
; #define PG8_WAIT_L(n) asm volatile("s_waitcnt lgkmcnt(" #n ")" ::: "memory")
; #define PG8_BAR __builtin_amdgcn_s_barrier()
; #define PG8_SCHED __builtin_amdgcn_sched_barrier(0)
;     ...
;             PG8_LDB(B0, 0, 0); PG8_LDB(B1, 0, 1); PG8_SCHED; PG8_LDA(At, 0, 0); PG8_STAGE(PG8_SA(1, 1), a1 + hstep, voffA);
;             PG8_WAIT_V(8); PG8_WAIT_L(0); PG8_BAR; PG8_MMAF(0, 0, At, B0); PG8_MMAF(0, 1, At, B1); PG8_BAR; PG8_SCHED;
;             const bool fin = last && !has_next;
;             PG8_LDA(At, 0, 1); if (!fin) { PG8_STAGE(PG8_SB(0, 0), b2, voffB); PG8_STAGE(PG8_SB(0, 1), b2 + hstep, voffB); PG8_STAGE(PG8_SA(0, 0), a2, voffA); }
;             if (!fin) PG8_WAIT_V(8); else PG8_WAIT_V(2); PG8_WAIT_L(0); PG8_BAR; PG8_MMAF(1, 0, At, B0); PG8_MMAF(1, 1, At, B1); PG8_BAR; PG8_SCHED;
.LBB0_1111:
	s_ashr_i32 s43, s42, 31
	s_lshl_b64 s[8:9], s[42:43], 19
	s_add_u32 s44, s74, s8
	s_addc_u32 s45, s75, s9
	s_and_b64 s[8:9], exec, s[4:5]
	s_waitcnt lgkmcnt(0)
	ds_read_b128 v[2:5], v201
	ds_read_b128 v[6:9], v201 offset:1024
	ds_read_b128 v[10:13], v201 offset:2048
	ds_read_b128 v[14:17], v201 offset:3072
	ds_read_b128 v[18:21], v202
	ds_read_b128 v[22:25], v202 offset:1024
	ds_read_b128 v[26:29], v202 offset:2048
	ds_read_b128 v[30:33], v202 offset:3072
	s_cselect_b32 s43, s55, s45
	s_cselect_b32 s56, s54, s44
	s_ashr_i32 s41, s40, 31
	s_lshl_b64 s[8:9], s[40:41], 19
	s_add_u32 s46, s94, s8
	s_addc_u32 s47, s95, s9
	s_and_b64 s[8:9], exec, s[4:5]
	s_cselect_b32 s41, s7, s47
	s_cselect_b32 s57, s6, s46
	s_add_u32 s52, s54, 0x100
	s_addc_u32 s53, s55, 0
	s_add_u32 s26, s6, 0x100
	s_addc_u32 s27, s7, 0
	s_add_u32 s8, s54, 0x180
	s_addc_u32 s9, s55, 0
	ds_read_b128 v[34:37], v203
	ds_read_b128 v[38:41], v203 offset:1024
	ds_read_b128 v[42:45], v203 offset:2048
	ds_read_b128 v[46:49], v203 offset:3072
	ds_read_b128 v[50:53], v203 offset:4096
	ds_read_b128 v[54:57], v203 offset:5120
	ds_read_b128 v[58:61], v203 offset:6144
	ds_read_b128 v[62:65], v203 offset:7168
	s_add_u32 s24, s6, 0x180
	s_addc_u32 s25, s7, 0
	s_add_u32 s58, s54, 0x40080
	s_addc_u32 s59, s55, 0
	s_add_u32 m0, s28, 0xc000
	s_nop 0
	global_load_lds_dwordx4 v1, s[58:59]
	s_nop 0
	s_add_u32 m0, s28, 0xe000
	s_nop 0
	global_load_lds_dwordx4 v199, s[58:59]
	s_waitcnt vmcnt(8)
	s_waitcnt lgkmcnt(0)
	s_barrier
	v_mfma_f32_16x16x32_f16 v[90:93], v[2:5], v[58:61], 0
	s_setprio 1
	v_mfma_f32_16x16x32_f16 v[98:101], v[6:9], v[62:65], v[90:93]
	v_mfma_f32_16x16x32_f16 v[66:69], v[6:9], v[38:41], 0
	v_mfma_f32_16x16x32_f16 v[66:69], v[2:5], v[34:37], v[66:69]
	v_mfma_f32_16x16x32_f16 v[70:73], v[10:13], v[34:37], 0
	v_mfma_f32_16x16x32_f16 v[70:73], v[14:17], v[38:41], v[70:73]
	v_mfma_f32_16x16x32_f16 v[78:81], v[14:17], v[46:49], 0
	v_mfma_f32_16x16x32_f16 v[78:81], v[10:13], v[42:45], v[78:81]
	v_mfma_f32_16x16x32_f16 v[74:77], v[2:5], v[42:45], 0
	v_mfma_f32_16x16x32_f16 v[74:77], v[6:9], v[46:49], v[74:77]
	v_mfma_f32_16x16x32_f16 v[82:85], v[6:9], v[54:57], 0
	v_mfma_f32_16x16x32_f16 v[82:85], v[2:5], v[50:53], v[82:85]
	v_mfma_f32_16x16x32_f16 v[86:89], v[10:13], v[50:53], 0
	v_mfma_f32_16x16x32_f16 v[86:89], v[14:17], v[54:57], v[86:89]
	v_mfma_f32_16x16x32_f16 v[90:93], v[14:17], v[62:65], 0
	v_mfma_f32_16x16x32_f16 v[102:105], v[10:13], v[58:61], v[90:93]
	v_mfma_f32_16x16x32_f16 v[90:93], v[18:21], v[34:37], 0
	v_mfma_f32_16x16x32_f16 v[114:117], v[22:25], v[38:41], v[90:93]
	v_mfma_f32_16x16x32_f16 v[34:37], v[26:29], v[34:37], 0
	v_mfma_f32_16x16x32_f16 v[34:37], v[30:33], v[38:41], v[34:37]
	v_mfma_f32_16x16x32_f16 v[38:41], v[18:21], v[42:45], 0
	v_mfma_f32_16x16x32_f16 v[38:41], v[22:25], v[46:49], v[38:41]
	v_mfma_f32_16x16x32_f16 v[42:45], v[26:29], v[42:45], 0
	v_mfma_f32_16x16x32_f16 v[42:45], v[30:33], v[46:49], v[42:45]
	v_mfma_f32_16x16x32_f16 v[46:49], v[18:21], v[50:53], 0
	v_mfma_f32_16x16x32_f16 v[46:49], v[22:25], v[54:57], v[46:49]
	v_mfma_f32_16x16x32_f16 v[50:53], v[26:29], v[50:53], 0
	v_mfma_f32_16x16x32_f16 v[50:53], v[30:33], v[54:57], v[50:53]
	v_mfma_f32_16x16x32_f16 v[54:57], v[18:21], v[58:61], 0
	v_mfma_f32_16x16x32_f16 v[54:57], v[22:25], v[62:65], v[54:57]
	v_mfma_f32_16x16x32_f16 v[58:61], v[26:29], v[58:61], 0
	v_mfma_f32_16x16x32_f16 v[58:61], v[30:33], v[62:65], v[58:61]
	s_barrier
	s_setprio 0
	ds_read_b128 v[62:65], v203 offset:16384
	ds_read_b128 v[90:93], v203 offset:17408
	ds_read_b128 v[94:97], v203 offset:18432
	ds_read_b128 v[106:109], v203 offset:19456
	ds_read_b128 v[110:113], v203 offset:20480
	ds_read_b128 v[118:121], v203 offset:21504
	ds_read_b128 v[122:125], v203 offset:22528
	ds_read_b128 v[126:129], v203 offset:23552
	s_add_u32 m0, s28, 0x10000
	s_nop 0
	global_load_lds_dwordx4 v198, s[26:27]
	s_nop 0
	s_add_u32 m0, s28, 0x12000
	s_nop 0
	global_load_lds_dwordx4 v200, s[26:27]
	s_add_u32 s26, s6, 0x40100
	s_addc_u32 s27, s7, 0
	s_add_u32 m0, s28, 0x14000
	s_nop 0
	global_load_lds_dwordx4 v198, s[26:27]
	s_nop 0
	s_add_u32 m0, s28, 0x16000
	s_nop 0
	global_load_lds_dwordx4 v200, s[26:27]
	s_nop 0
	s_add_u32 m0, s28, 0
	s_nop 0
	global_load_lds_dwordx4 v1, s[52:53]
	s_nop 0
	s_add_u32 m0, s28, 0x2000
	s_nop 0
	global_load_lds_dwordx4 v199, s[52:53]
	s_waitcnt vmcnt(8)
	s_waitcnt lgkmcnt(0)
	s_barrier
	v_mfma_f32_16x16x32_f16 v[130:133], v[2:5], v[62:65], 0
	s_setprio 1
	v_mfma_f32_16x16x32_f16 v[130:133], v[6:9], v[90:93], v[130:133]
	v_mfma_f32_16x16x32_f16 v[138:141], v[2:5], v[94:97], 0
	v_mfma_f32_16x16x32_f16 v[138:141], v[6:9], v[106:109], v[138:141]
	v_mfma_f32_16x16x32_f16 v[146:149], v[2:5], v[110:113], 0
	v_mfma_f32_16x16x32_f16 v[146:149], v[6:9], v[118:121], v[146:149]
	v_mfma_f32_16x16x32_f16 v[2:5], v[2:5], v[122:125], 0
	v_mfma_f32_16x16x32_f16 v[2:5], v[6:9], v[126:129], v[2:5]
	v_mfma_f32_16x16x32_f16 v[6:9], v[10:13], v[122:125], 0
	v_mfma_f32_16x16x32_f16 v[6:9], v[14:17], v[126:129], v[6:9]
	v_mfma_f32_16x16x32_f16 v[134:137], v[10:13], v[62:65], 0
	v_mfma_f32_16x16x32_f16 v[134:137], v[14:17], v[90:93], v[134:137]
	v_mfma_f32_16x16x32_f16 v[142:145], v[10:13], v[94:97], 0
	v_mfma_f32_16x16x32_f16 v[142:145], v[14:17], v[106:109], v[142:145]
	v_mfma_f32_16x16x32_f16 v[150:153], v[10:13], v[110:113], 0
	v_mfma_f32_16x16x32_f16 v[150:153], v[14:17], v[118:121], v[150:153]
	v_mfma_f32_16x16x32_f16 v[10:13], v[18:21], v[62:65], 0
	v_mfma_f32_16x16x32_f16 v[154:157], v[22:25], v[90:93], v[10:13]
	v_mfma_f32_16x16x32_f16 v[10:13], v[26:29], v[62:65], 0
	v_mfma_f32_16x16x32_f16 v[158:161], v[30:33], v[90:93], v[10:13]
	v_mfma_f32_16x16x32_f16 v[10:13], v[18:21], v[94:97], 0
	v_mfma_f32_16x16x32_f16 v[162:165], v[22:25], v[106:109], v[10:13]
	v_mfma_f32_16x16x32_f16 v[10:13], v[26:29], v[94:97], 0
	v_mfma_f32_16x16x32_f16 v[166:169], v[30:33], v[106:109], v[10:13]
	v_mfma_f32_16x16x32_f16 v[10:13], v[18:21], v[110:113], 0
	v_mfma_f32_16x16x32_f16 v[170:173], v[22:25], v[118:121], v[10:13]
	v_mfma_f32_16x16x32_f16 v[10:13], v[26:29], v[110:113], 0
	v_mfma_f32_16x16x32_f16 v[174:177], v[30:33], v[118:121], v[10:13]
	v_mfma_f32_16x16x32_f16 v[10:13], v[18:21], v[122:125], 0
	v_mfma_f32_16x16x32_f16 v[178:181], v[22:25], v[126:129], v[10:13]
	v_mfma_f32_16x16x32_f16 v[10:13], v[26:29], v[122:125], 0
	v_mfma_f32_16x16x32_f16 v[182:185], v[30:33], v[126:129], v[10:13]
	s_barrier
; #define PG8_STAGE(bufoff, gbase, voff) do { if constexpr (ABL & 1) break; glds16s<(bufoff)>((voff)[0], (const void*)(gbase), ldsbw); glds16s<(bufoff) + 8192>((voff)[1], (const void*)(gbase), ldsbw); } while (0)
; #define PG8_LDA(dst, b, h) do { if constexpr (ABL & 4) break; _Pragma("unroll") for (int m = 0; m < 4; ++m) _Pragma("unroll") for (int k = 0; k < 2; ++k) dst[m][k] = *(const LAS f16x8*)(lds + PG8_SA(b, h) + aoff + m * 2048 + k * 1024); } while (0)
; #define PG8_LDB(dst, b, h) do { if constexpr (ABL & 4) break; _Pragma("unroll") for (int n = 0; n < 2; ++n) _Pragma("unroll") for (int k = 0; k < 2; ++k) dst[n][k] = *(const LAS f16x8*)(lds + PG8_SB(b, h) + boff + n * 2048 + k * 1024); } while (0)
; #define PG8_MMA(ai, bj, At, Bt) do { if constexpr (ABL & 2) break; __builtin_amdgcn_s_setprio(1); _Pragma("unroll") for (int m = 0; m < 4; ++m) _Pragma("unroll") for (int n = 0; n < 2; ++n) _Pragma("unroll") for (int k = 0; k < 2; ++k) \
;         acc[ai][bj][m][n] = __builtin_amdgcn_mfma_f32_16x16x32_f16(Bt[n][k], At[m][k], acc[ai][bj][m][n], 0, 0, 0); __builtin_amdgcn_s_setprio(0); } while (0)
; #define PG8_WAIT_V(n) asm volatile("s_waitcnt vmcnt(" #n ")" ::: "memory")
; #define PG8_WAIT_L(n) asm volatile("s_waitcnt lgkmcnt(" #n ")" ::: "memory")
; #define PG8_BAR __builtin_amdgcn_s_barrier()
; #define PG8_SCHED __builtin_amdgcn_sched_barrier(0)
;     ...
;             PG8_LDB(B0, 1, 0); PG8_LDB(B1, 1, 1); PG8_SCHED; PG8_LDA(At, 1, 0); if (!fin) PG8_STAGE(PG8_SA(0, 1), a2 + hstep, voffA);
;             if (!fin) PG8_WAIT_V(8); else PG8_WAIT_V(0); PG8_WAIT_L(0); PG8_BAR; PG8_MMA(0, 0, At, B0); PG8_MMA(0, 1, At, B1); PG8_BAR; PG8_SCHED;
;             PG8_LDA(At, 1, 1); if (!fin) { PG8_STAGE(PG8_SB(1, 0), b3, voffB); PG8_STAGE(PG8_SB(1, 1), b3 + hstep, voffB); PG8_STAGE(PG8_SA(1, 0), a3, voffA); }
;             if (!fin) PG8_WAIT_V(8); PG8_WAIT_L(0); PG8_BAR; PG8_MMA(1, 0, At, B0); PG8_MMA(1, 1, At, B1); PG8_BAR; PG8_SCHED;
	s_setprio 0
	s_nop 4
	ds_read_b128 v[10:13], v204
	ds_read_b128 v[14:17], v204 offset:1024
	ds_read_b128 v[18:21], v204 offset:2048
	ds_read_b128 v[22:25], v204 offset:3072
	ds_read_b128 v[186:189], v205
	ds_read_b128 v[190:193], v205 offset:1024
	ds_read_b128 v[210:213], v205 offset:2048
	ds_read_b128 v[214:217], v205 offset:3072
	ds_read_b128 v[26:29], v203 offset:32768
	ds_read_b128 v[30:33], v203 offset:33792
	ds_read_b128 v[62:65], v203 offset:34816
	ds_read_b128 v[218:221], v203 offset:35840
	ds_read_b128 v[222:225], v203 offset:36864
	ds_read_b128 v[226:229], v203 offset:37888
	ds_read_b128 v[230:233], v203 offset:38912
	ds_read_b128 v[234:237], v203 offset:39936
	s_add_u32 s26, s54, 0x40100
	s_addc_u32 s27, s55, 0
	s_add_u32 m0, s28, 0x4000
	s_nop 0
	global_load_lds_dwordx4 v1, s[26:27]
	s_nop 0
	s_add_u32 m0, s28, 0x6000
	s_nop 0
	global_load_lds_dwordx4 v199, s[26:27]
	s_waitcnt vmcnt(8)
	s_waitcnt lgkmcnt(0)
	s_barrier
	v_mfma_f32_16x16x32_f16 v[66:69], v[10:13], v[26:29], v[66:69]
	s_setprio 1
	v_mfma_f32_16x16x32_f16 v[126:129], v[14:17], v[30:33], v[66:69]
	v_mfma_f32_16x16x32_f16 v[66:69], v[18:21], v[26:29], v[70:73]
	v_mfma_f32_16x16x32_f16 v[122:125], v[22:25], v[30:33], v[66:69]
	v_mfma_f32_16x16x32_f16 v[66:69], v[10:13], v[62:65], v[74:77]
	v_mfma_f32_16x16x32_f16 v[110:113], v[14:17], v[218:221], v[66:69]
	v_mfma_f32_16x16x32_f16 v[66:69], v[18:21], v[62:65], v[78:81]
	v_mfma_f32_16x16x32_f16 v[106:109], v[22:25], v[218:221], v[66:69]
	v_mfma_f32_16x16x32_f16 v[66:69], v[10:13], v[222:225], v[82:85]
	v_mfma_f32_16x16x32_f16 v[94:97], v[14:17], v[226:229], v[66:69]
	v_mfma_f32_16x16x32_f16 v[66:69], v[18:21], v[222:225], v[86:89]
	v_mfma_f32_16x16x32_f16 v[90:93], v[22:25], v[226:229], v[66:69]
	v_mfma_f32_16x16x32_f16 v[66:69], v[10:13], v[230:233], v[98:101]
	v_mfma_f32_16x16x32_f16 v[78:81], v[14:17], v[234:237], v[66:69]
	v_mfma_f32_16x16x32_f16 v[66:69], v[18:21], v[230:233], v[102:105]
	v_mfma_f32_16x16x32_f16 v[74:77], v[22:25], v[234:237], v[66:69]
	v_mfma_f32_16x16x32_f16 v[66:69], v[186:189], v[26:29], v[114:117]
	v_mfma_f32_16x16x32_f16 v[118:121], v[190:193], v[30:33], v[66:69]
	v_mfma_f32_16x16x32_f16 v[26:29], v[210:213], v[26:29], v[34:37]
	v_mfma_f32_16x16x32_f16 v[114:117], v[214:217], v[30:33], v[26:29]
	v_mfma_f32_16x16x32_f16 v[26:29], v[186:189], v[62:65], v[38:41]
	v_mfma_f32_16x16x32_f16 v[102:105], v[190:193], v[218:221], v[26:29]
	v_mfma_f32_16x16x32_f16 v[26:29], v[210:213], v[62:65], v[42:45]
	v_mfma_f32_16x16x32_f16 v[98:101], v[214:217], v[218:221], v[26:29]
	v_mfma_f32_16x16x32_f16 v[26:29], v[186:189], v[222:225], v[46:49]
	v_mfma_f32_16x16x32_f16 v[86:89], v[190:193], v[226:229], v[26:29]
	v_mfma_f32_16x16x32_f16 v[26:29], v[210:213], v[222:225], v[50:53]
	v_mfma_f32_16x16x32_f16 v[82:85], v[214:217], v[226:229], v[26:29]
	v_mfma_f32_16x16x32_f16 v[26:29], v[186:189], v[230:233], v[54:57]
	v_mfma_f32_16x16x32_f16 v[70:73], v[190:193], v[234:237], v[26:29]
	v_mfma_f32_16x16x32_f16 v[26:29], v[210:213], v[230:233], v[58:61]
	v_mfma_f32_16x16x32_f16 v[66:69], v[214:217], v[234:237], v[26:29]
	s_barrier
	s_setprio 0
	ds_read_b128 v[34:37], v203 offset:49152
	ds_read_b128 v[38:41], v203 offset:50176
	ds_read_b128 v[218:221], v203 offset:51200
	ds_read_b128 v[222:225], v203 offset:52224
	ds_read_b128 v[226:229], v203 offset:53248
	ds_read_b128 v[230:233], v203 offset:54272
	ds_read_b128 v[234:237], v203 offset:55296
	ds_read_b128 v[238:241], v203 offset:56320
	s_add_u32 m0, s28, 0x18000
	s_nop 0
	global_load_lds_dwordx4 v198, s[24:25]
	s_nop 0
	s_add_u32 m0, s28, 0x1a000
	s_nop 0
	global_load_lds_dwordx4 v200, s[24:25]
	s_add_u32 s24, s6, 0x40180
	s_addc_u32 s25, s7, 0
	s_add_u32 m0, s28, 0x1c000
	s_nop 0
	global_load_lds_dwordx4 v198, s[24:25]
	s_nop 0
	s_add_u32 m0, s28, 0x1e000
	s_nop 0
	global_load_lds_dwordx4 v200, s[24:25]
	s_nop 0
	s_add_u32 m0, s28, 0x8000
	s_nop 0
	global_load_lds_dwordx4 v1, s[8:9]
	s_nop 0
	s_add_u32 m0, s28, 0xa000
	s_nop 0
	global_load_lds_dwordx4 v199, s[8:9]
	s_waitcnt vmcnt(8)
	s_waitcnt lgkmcnt(0)
	s_barrier
	v_mfma_f32_16x16x32_f16 v[26:29], v[10:13], v[34:37], v[130:133]
	s_setprio 1
	v_mfma_f32_16x16x32_f16 v[62:65], v[14:17], v[38:41], v[26:29]
	v_mfma_f32_16x16x32_f16 v[26:29], v[22:25], v[38:41], v[134:137]
	v_mfma_f32_16x16x32_f16 v[58:61], v[18:21], v[34:37], v[26:29]
	v_mfma_f32_16x16x32_f16 v[26:29], v[10:13], v[218:221], v[138:141]
	v_mfma_f32_16x16x32_f16 v[46:49], v[14:17], v[222:225], v[26:29]
	v_mfma_f32_16x16x32_f16 v[26:29], v[22:25], v[222:225], v[142:145]
	v_mfma_f32_16x16x32_f16 v[42:45], v[18:21], v[218:221], v[26:29]
	v_mfma_f32_16x16x32_f16 v[26:29], v[10:13], v[226:229], v[146:149]
	v_mfma_f32_16x16x32_f16 v[30:33], v[14:17], v[230:233], v[26:29]
	v_mfma_f32_16x16x32_f16 v[26:29], v[22:25], v[230:233], v[150:153]
	v_mfma_f32_16x16x32_f16 v[26:29], v[18:21], v[226:229], v[26:29]
	v_mfma_f32_16x16x32_f16 v[2:5], v[10:13], v[234:237], v[2:5]
	v_mfma_f32_16x16x32_f16 v[14:17], v[14:17], v[238:241], v[2:5]
	v_mfma_f32_16x16x32_f16 v[2:5], v[22:25], v[238:241], v[6:9]
	v_mfma_f32_16x16x32_f16 v[10:13], v[18:21], v[234:237], v[2:5]
	v_mfma_f32_16x16x32_f16 v[2:5], v[186:189], v[34:37], v[154:157]
	v_mfma_f32_16x16x32_f16 v[54:57], v[190:193], v[38:41], v[2:5]
	v_mfma_f32_16x16x32_f16 v[2:5], v[214:217], v[38:41], v[158:161]
	v_mfma_f32_16x16x32_f16 v[50:53], v[210:213], v[34:37], v[2:5]
	v_mfma_f32_16x16x32_f16 v[2:5], v[186:189], v[218:221], v[162:165]
	v_mfma_f32_16x16x32_f16 v[38:41], v[190:193], v[222:225], v[2:5]
	v_mfma_f32_16x16x32_f16 v[2:5], v[214:217], v[222:225], v[166:169]
	v_mfma_f32_16x16x32_f16 v[34:37], v[210:213], v[218:221], v[2:5]
	v_mfma_f32_16x16x32_f16 v[2:5], v[186:189], v[226:229], v[170:173]
	v_mfma_f32_16x16x32_f16 v[22:25], v[190:193], v[230:233], v[2:5]
	v_mfma_f32_16x16x32_f16 v[2:5], v[214:217], v[230:233], v[174:177]
	v_mfma_f32_16x16x32_f16 v[18:21], v[210:213], v[226:229], v[2:5]
	v_mfma_f32_16x16x32_f16 v[2:5], v[186:189], v[234:237], v[178:181]
	v_mfma_f32_16x16x32_f16 v[6:9], v[190:193], v[238:241], v[2:5]
	v_mfma_f32_16x16x32_f16 v[2:5], v[214:217], v[238:241], v[182:185]
	v_mfma_f32_16x16x32_f16 v[2:5], v[210:213], v[234:237], v[2:5]
	s_barrier
	s_setprio 0
	s_add_u32 s54, s6, 0x200
	s_addc_u32 s55, s7, 0
	s_mov_b32 s58, 0
	s_branch .LBB0_1113

; #define PG8_STAGE(bufoff, gbase, voff) do { if constexpr (ABL & 1) break; glds16s<(bufoff)>((voff)[0], (const void*)(gbase), ldsbw); glds16s<(bufoff) + 8192>((voff)[1], (const void*)(gbase), ldsbw); } while (0)
; #define PG8_LDA(dst, b, h) do { if constexpr (ABL & 4) break; _Pragma("unroll") for (int m = 0; m < 4; ++m) _Pragma("unroll") for (int k = 0; k < 2; ++k) dst[m][k] = *(const LAS f16x8*)(lds + PG8_SA(b, h) + aoff + m * 2048 + k * 1024); } while (0)
; #define PG8_LDB(dst, b, h) do { if constexpr (ABL & 4) break; _Pragma("unroll") for (int n = 0; n < 2; ++n) _Pragma("unroll") for (int k = 0; k < 2; ++k) dst[n][k] = *(const LAS f16x8*)(lds + PG8_SB(b, h) + boff + n * 2048 + k * 1024); } while (0)
; #define PG8_MMAF(ai, bj, At, Bt) do { if (t == 0) PG8_MMA0(ai, bj, At, Bt); else PG8_MMA(ai, bj, At, Bt); } while (0)
; #define PG8_WAIT_V(n) asm volatile("s_waitcnt vmcnt(" #n ")" ::: "memory")
; #define PG8_WAIT_L(n) asm volatile("s_waitcnt lgkmcnt(" #n ")" ::: "memory")
; #define PG8_BAR __builtin_amdgcn_s_barrier()
; #define PG8_SCHED __builtin_amdgcn_sched_barrier(0)
;     ...
;             PG8_LDB(B0, 0, 0); PG8_LDB(B1, 0, 1); PG8_SCHED; PG8_LDA(At, 0, 0); PG8_STAGE(PG8_SA(1, 1), a1 + hstep, voffA);
;             PG8_WAIT_V(8); PG8_WAIT_L(0); PG8_BAR; PG8_MMAF(0, 0, At, B0); PG8_MMAF(0, 1, At, B1); PG8_BAR; PG8_SCHED;
;             const bool fin = last && !has_next;
;             PG8_LDA(At, 0, 1); if (!fin) { PG8_STAGE(PG8_SB(0, 0), b2, voffB); PG8_STAGE(PG8_SB(0, 1), b2 + hstep, voffB); PG8_STAGE(PG8_SA(0, 0), a2, voffA); }
;             if (!fin) PG8_WAIT_V(8); else PG8_WAIT_V(2); PG8_WAIT_L(0); PG8_BAR; PG8_MMAF(1, 0, At, B0); PG8_MMAF(1, 1, At, B1); PG8_BAR; PG8_SCHED;
.LBB0_1163:
	s_ashr_i32 s49, s48, 31
	s_lshl_b64 s[6:7], s[48:49], 19
	s_add_u32 s50, s74, s6
	s_addc_u32 s51, s75, s7
	s_and_b64 s[6:7], exec, s[2:3]
	ds_read_b128 v[2:5], v213
	ds_read_b128 v[6:9], v213 offset:1024
	ds_read_b128 v[10:13], v213 offset:2048
	ds_read_b128 v[14:17], v213 offset:3072
	ds_read_b128 v[18:21], v214
	ds_read_b128 v[22:25], v214 offset:1024
	ds_read_b128 v[26:29], v214 offset:2048
	ds_read_b128 v[30:33], v214 offset:3072
	s_cselect_b32 s45, s37, s51
	s_cselect_b32 s49, s36, s50
	s_ashr_i32 s47, s46, 31
	s_lshl_b64 s[6:7], s[46:47], 19
	s_add_u32 s52, s94, s6
	s_addc_u32 s53, s95, s7
	s_and_b64 s[6:7], exec, s[2:3]
	s_cselect_b32 s47, s39, s53
	s_cselect_b32 s57, s38, s52
	s_add_u32 s24, s36, 0x100
	s_addc_u32 s25, s37, 0
	s_add_u32 s26, s38, 0x100
	s_addc_u32 s27, s39, 0
	s_add_u32 s6, s36, 0x180
	s_addc_u32 s7, s37, 0
	ds_read_b128 v[34:37], v215
	ds_read_b128 v[38:41], v215 offset:1024
	ds_read_b128 v[42:45], v215 offset:2048
	ds_read_b128 v[46:49], v215 offset:3072
	ds_read_b128 v[50:53], v215 offset:4096
	ds_read_b128 v[54:57], v215 offset:5120
	ds_read_b128 v[58:61], v215 offset:6144
	ds_read_b128 v[62:65], v215 offset:7168
	s_add_u32 s8, s38, 0x180
	s_addc_u32 s9, s39, 0
	s_add_u32 s54, s36, 0x40080
	s_addc_u32 s55, s37, 0
	s_add_u32 m0, s35, 0xc000
	s_nop 0
	global_load_lds_dwordx4 v1, s[54:55]
	s_nop 0
	s_add_u32 m0, s35, 0xe000
	s_nop 0
	global_load_lds_dwordx4 v211, s[54:55]
	s_waitcnt vmcnt(8)
	s_waitcnt lgkmcnt(0)
	s_barrier
	v_mfma_f32_16x16x32_f16 v[90:93], v[2:5], v[58:61], 0
	s_setprio 1
	v_mfma_f32_16x16x32_f16 v[98:101], v[6:9], v[62:65], v[90:93]
	v_mfma_f32_16x16x32_f16 v[66:69], v[6:9], v[38:41], 0
	v_mfma_f32_16x16x32_f16 v[66:69], v[2:5], v[34:37], v[66:69]
	v_mfma_f32_16x16x32_f16 v[70:73], v[10:13], v[34:37], 0
	v_mfma_f32_16x16x32_f16 v[70:73], v[14:17], v[38:41], v[70:73]
	v_mfma_f32_16x16x32_f16 v[78:81], v[14:17], v[46:49], 0
	v_mfma_f32_16x16x32_f16 v[78:81], v[10:13], v[42:45], v[78:81]
	v_mfma_f32_16x16x32_f16 v[74:77], v[2:5], v[42:45], 0
	v_mfma_f32_16x16x32_f16 v[74:77], v[6:9], v[46:49], v[74:77]
	v_mfma_f32_16x16x32_f16 v[82:85], v[6:9], v[54:57], 0
	v_mfma_f32_16x16x32_f16 v[82:85], v[2:5], v[50:53], v[82:85]
	v_mfma_f32_16x16x32_f16 v[86:89], v[10:13], v[50:53], 0
	v_mfma_f32_16x16x32_f16 v[86:89], v[14:17], v[54:57], v[86:89]
	v_mfma_f32_16x16x32_f16 v[90:93], v[14:17], v[62:65], 0
	v_mfma_f32_16x16x32_f16 v[102:105], v[10:13], v[58:61], v[90:93]
	v_mfma_f32_16x16x32_f16 v[90:93], v[18:21], v[34:37], 0
	v_mfma_f32_16x16x32_f16 v[114:117], v[22:25], v[38:41], v[90:93]
	v_mfma_f32_16x16x32_f16 v[34:37], v[26:29], v[34:37], 0
	v_mfma_f32_16x16x32_f16 v[34:37], v[30:33], v[38:41], v[34:37]
	v_mfma_f32_16x16x32_f16 v[38:41], v[18:21], v[42:45], 0
	v_mfma_f32_16x16x32_f16 v[38:41], v[22:25], v[46:49], v[38:41]
	v_mfma_f32_16x16x32_f16 v[42:45], v[26:29], v[42:45], 0
	v_mfma_f32_16x16x32_f16 v[42:45], v[30:33], v[46:49], v[42:45]
	v_mfma_f32_16x16x32_f16 v[46:49], v[18:21], v[50:53], 0
	v_mfma_f32_16x16x32_f16 v[46:49], v[22:25], v[54:57], v[46:49]
	v_mfma_f32_16x16x32_f16 v[50:53], v[26:29], v[50:53], 0
	v_mfma_f32_16x16x32_f16 v[50:53], v[30:33], v[54:57], v[50:53]
	v_mfma_f32_16x16x32_f16 v[54:57], v[18:21], v[58:61], 0
	v_mfma_f32_16x16x32_f16 v[54:57], v[22:25], v[62:65], v[54:57]
	v_mfma_f32_16x16x32_f16 v[58:61], v[26:29], v[58:61], 0
	v_mfma_f32_16x16x32_f16 v[58:61], v[30:33], v[62:65], v[58:61]
	s_barrier
	s_setprio 0
	ds_read_b128 v[62:65], v215 offset:16384
	ds_read_b128 v[90:93], v215 offset:17408
	ds_read_b128 v[94:97], v215 offset:18432
	ds_read_b128 v[106:109], v215 offset:19456
	ds_read_b128 v[110:113], v215 offset:20480
	ds_read_b128 v[118:121], v215 offset:21504
	ds_read_b128 v[122:125], v215 offset:22528
	ds_read_b128 v[126:129], v215 offset:23552
	s_add_u32 m0, s35, 0x10000
	s_nop 0
	global_load_lds_dwordx4 v210, s[26:27]
	s_nop 0
	s_add_u32 m0, s35, 0x12000
	s_nop 0
	global_load_lds_dwordx4 v212, s[26:27]
	s_add_u32 s26, s38, 0x40100
	s_addc_u32 s27, s39, 0
	s_add_u32 m0, s35, 0x14000
	s_nop 0
	global_load_lds_dwordx4 v210, s[26:27]
	s_nop 0
	s_add_u32 m0, s35, 0x16000
	s_nop 0
	global_load_lds_dwordx4 v212, s[26:27]
	s_nop 0
	s_add_u32 m0, s35, 0
	s_nop 0
	global_load_lds_dwordx4 v1, s[24:25]
	s_nop 0
	s_add_u32 m0, s35, 0x2000
	s_nop 0
	global_load_lds_dwordx4 v211, s[24:25]
	s_waitcnt vmcnt(8)
	s_waitcnt lgkmcnt(0)
	s_barrier
	v_mfma_f32_16x16x32_f16 v[134:137], v[10:13], v[62:65], 0
	s_setprio 1
	v_mfma_f32_16x16x32_f16 v[146:149], v[14:17], v[90:93], v[134:137]
	v_mfma_f32_16x16x32_f16 v[134:137], v[2:5], v[94:97], 0
	v_mfma_f32_16x16x32_f16 v[150:153], v[6:9], v[106:109], v[134:137]
	v_mfma_f32_16x16x32_f16 v[134:137], v[10:13], v[94:97], 0
	v_mfma_f32_16x16x32_f16 v[154:157], v[14:17], v[106:109], v[134:137]
	v_mfma_f32_16x16x32_f16 v[130:133], v[2:5], v[62:65], 0
	v_mfma_f32_16x16x32_f16 v[130:133], v[6:9], v[90:93], v[130:133]
	v_mfma_f32_16x16x32_f16 v[134:137], v[2:5], v[110:113], 0
	v_mfma_f32_16x16x32_f16 v[158:161], v[6:9], v[118:121], v[134:137]
	v_mfma_f32_16x16x32_f16 v[2:5], v[2:5], v[122:125], 0
	v_mfma_f32_16x16x32_f16 v[2:5], v[6:9], v[126:129], v[2:5]
	v_mfma_f32_16x16x32_f16 v[6:9], v[10:13], v[122:125], 0
	v_mfma_f32_16x16x32_f16 v[6:9], v[14:17], v[126:129], v[6:9]
	v_mfma_f32_16x16x32_f16 v[134:137], v[10:13], v[110:113], 0
	v_mfma_f32_16x16x32_f16 v[162:165], v[14:17], v[118:121], v[134:137]
	v_mfma_f32_16x16x32_f16 v[10:13], v[18:21], v[62:65], 0
	v_mfma_f32_16x16x32_f16 v[166:169], v[22:25], v[90:93], v[10:13]
	v_mfma_f32_16x16x32_f16 v[10:13], v[26:29], v[62:65], 0
	v_mfma_f32_16x16x32_f16 v[170:173], v[30:33], v[90:93], v[10:13]
	v_mfma_f32_16x16x32_f16 v[10:13], v[18:21], v[94:97], 0
	v_mfma_f32_16x16x32_f16 v[174:177], v[22:25], v[106:109], v[10:13]
	v_mfma_f32_16x16x32_f16 v[10:13], v[26:29], v[94:97], 0
	v_mfma_f32_16x16x32_f16 v[178:181], v[30:33], v[106:109], v[10:13]
	v_mfma_f32_16x16x32_f16 v[10:13], v[18:21], v[110:113], 0
	v_mfma_f32_16x16x32_f16 v[182:185], v[22:25], v[118:121], v[10:13]
	v_mfma_f32_16x16x32_f16 v[10:13], v[26:29], v[110:113], 0
	v_mfma_f32_16x16x32_f16 v[118:121], v[30:33], v[118:121], v[10:13]
	v_mfma_f32_16x16x32_f16 v[10:13], v[18:21], v[122:125], 0
	v_mfma_f32_16x16x32_f16 v[186:189], v[22:25], v[126:129], v[10:13]
	v_mfma_f32_16x16x32_f16 v[10:13], v[26:29], v[122:125], 0
	v_mfma_f32_16x16x32_f16 v[122:125], v[30:33], v[126:129], v[10:13]
	s_barrier
; #define PG8_STAGE(bufoff, gbase, voff) do { if constexpr (ABL & 1) break; glds16s<(bufoff)>((voff)[0], (const void*)(gbase), ldsbw); glds16s<(bufoff) + 8192>((voff)[1], (const void*)(gbase), ldsbw); } while (0)
; #define PG8_LDA(dst, b, h) do { if constexpr (ABL & 4) break; _Pragma("unroll") for (int m = 0; m < 4; ++m) _Pragma("unroll") for (int k = 0; k < 2; ++k) dst[m][k] = *(const LAS f16x8*)(lds + PG8_SA(b, h) + aoff + m * 2048 + k * 1024); } while (0)
; #define PG8_LDB(dst, b, h) do { if constexpr (ABL & 4) break; _Pragma("unroll") for (int n = 0; n < 2; ++n) _Pragma("unroll") for (int k = 0; k < 2; ++k) dst[n][k] = *(const LAS f16x8*)(lds + PG8_SB(b, h) + boff + n * 2048 + k * 1024); } while (0)
; #define PG8_MMA(ai, bj, At, Bt) do { if constexpr (ABL & 2) break; __builtin_amdgcn_s_setprio(1); _Pragma("unroll") for (int m = 0; m < 4; ++m) _Pragma("unroll") for (int n = 0; n < 2; ++n) _Pragma("unroll") for (int k = 0; k < 2; ++k) \
;         acc[ai][bj][m][n] = __builtin_amdgcn_mfma_f32_16x16x32_f16(Bt[n][k], At[m][k], acc[ai][bj][m][n], 0, 0, 0); __builtin_amdgcn_s_setprio(0); } while (0)
; #define PG8_WAIT_V(n) asm volatile("s_waitcnt vmcnt(" #n ")" ::: "memory")
; #define PG8_WAIT_L(n) asm volatile("s_waitcnt lgkmcnt(" #n ")" ::: "memory")
; #define PG8_BAR __builtin_amdgcn_s_barrier()
; #define PG8_SCHED __builtin_amdgcn_sched_barrier(0)
;     ...
;             PG8_LDB(B0, 1, 0); PG8_LDB(B1, 1, 1); PG8_SCHED; PG8_LDA(At, 1, 0); if (!fin) PG8_STAGE(PG8_SA(0, 1), a2 + hstep, voffA);
;             if (!fin) PG8_WAIT_V(8); else PG8_WAIT_V(0); PG8_WAIT_L(0); PG8_BAR; PG8_MMA(0, 0, At, B0); PG8_MMA(0, 1, At, B1); PG8_BAR; PG8_SCHED;
;             PG8_LDA(At, 1, 1); if (!fin) { PG8_STAGE(PG8_SB(1, 0), b3, voffB); PG8_STAGE(PG8_SB(1, 1), b3 + hstep, voffB); PG8_STAGE(PG8_SA(1, 0), a3, voffA); }
;             if (!fin) PG8_WAIT_V(8); PG8_WAIT_L(0); PG8_BAR; PG8_MMA(1, 0, At, B0); PG8_MMA(1, 1, At, B1); PG8_BAR; PG8_SCHED;
	s_setprio 0
	s_nop 4
	ds_read_b128 v[10:13], v216
	ds_read_b128 v[14:17], v216 offset:1024
	ds_read_b128 v[18:21], v216 offset:2048
	ds_read_b128 v[22:25], v216 offset:3072
	ds_read_b128 v[190:193], v217
	ds_read_b128 v[194:197], v217 offset:1024
	ds_read_b128 v[198:201], v217 offset:2048
	ds_read_b128 v[202:205], v217 offset:3072
	ds_read_b128 v[26:29], v215 offset:32768
	ds_read_b128 v[30:33], v215 offset:33792
	ds_read_b128 v[62:65], v215 offset:34816
	ds_read_b128 v[218:221], v215 offset:35840
	ds_read_b128 v[222:225], v215 offset:36864
	ds_read_b128 v[226:229], v215 offset:37888
	ds_read_b128 v[230:233], v215 offset:38912
	ds_read_b128 v[234:237], v215 offset:39936
	s_add_u32 s24, s36, 0x40100
	s_addc_u32 s25, s37, 0
	s_add_u32 m0, s35, 0x4000
	s_nop 0
	global_load_lds_dwordx4 v1, s[24:25]
	s_nop 0
	s_add_u32 m0, s35, 0x6000
	s_nop 0
	global_load_lds_dwordx4 v211, s[24:25]
	s_waitcnt vmcnt(8)
	s_waitcnt lgkmcnt(0)
	s_barrier
	v_mfma_f32_16x16x32_f16 v[66:69], v[10:13], v[26:29], v[66:69]
	s_setprio 1
	v_mfma_f32_16x16x32_f16 v[142:145], v[14:17], v[30:33], v[66:69]
	v_mfma_f32_16x16x32_f16 v[66:69], v[18:21], v[26:29], v[70:73]
	v_mfma_f32_16x16x32_f16 v[138:141], v[22:25], v[30:33], v[66:69]
	v_mfma_f32_16x16x32_f16 v[66:69], v[10:13], v[62:65], v[74:77]
	v_mfma_f32_16x16x32_f16 v[110:113], v[14:17], v[218:221], v[66:69]
	v_mfma_f32_16x16x32_f16 v[66:69], v[18:21], v[62:65], v[78:81]
	v_mfma_f32_16x16x32_f16 v[106:109], v[22:25], v[218:221], v[66:69]
	v_mfma_f32_16x16x32_f16 v[66:69], v[10:13], v[222:225], v[82:85]
	v_mfma_f32_16x16x32_f16 v[94:97], v[14:17], v[226:229], v[66:69]
	v_mfma_f32_16x16x32_f16 v[66:69], v[18:21], v[222:225], v[86:89]
	v_mfma_f32_16x16x32_f16 v[90:93], v[22:25], v[226:229], v[66:69]
	v_mfma_f32_16x16x32_f16 v[66:69], v[10:13], v[230:233], v[98:101]
	v_mfma_f32_16x16x32_f16 v[78:81], v[14:17], v[234:237], v[66:69]
	v_mfma_f32_16x16x32_f16 v[66:69], v[18:21], v[230:233], v[102:105]
	v_mfma_f32_16x16x32_f16 v[74:77], v[22:25], v[234:237], v[66:69]
	v_mfma_f32_16x16x32_f16 v[66:69], v[190:193], v[26:29], v[114:117]
	v_mfma_f32_16x16x32_f16 v[134:137], v[194:197], v[30:33], v[66:69]
	v_mfma_f32_16x16x32_f16 v[26:29], v[198:201], v[26:29], v[34:37]
	v_mfma_f32_16x16x32_f16 v[126:129], v[202:205], v[30:33], v[26:29]
	v_mfma_f32_16x16x32_f16 v[26:29], v[190:193], v[62:65], v[38:41]
	v_mfma_f32_16x16x32_f16 v[102:105], v[194:197], v[218:221], v[26:29]
	v_mfma_f32_16x16x32_f16 v[26:29], v[198:201], v[62:65], v[42:45]
	v_mfma_f32_16x16x32_f16 v[98:101], v[202:205], v[218:221], v[26:29]
	v_mfma_f32_16x16x32_f16 v[26:29], v[190:193], v[222:225], v[46:49]
	v_mfma_f32_16x16x32_f16 v[86:89], v[194:197], v[226:229], v[26:29]
	v_mfma_f32_16x16x32_f16 v[26:29], v[198:201], v[222:225], v[50:53]
	v_mfma_f32_16x16x32_f16 v[82:85], v[202:205], v[226:229], v[26:29]
	v_mfma_f32_16x16x32_f16 v[26:29], v[190:193], v[230:233], v[54:57]
	v_mfma_f32_16x16x32_f16 v[70:73], v[194:197], v[234:237], v[26:29]
	v_mfma_f32_16x16x32_f16 v[26:29], v[198:201], v[230:233], v[58:61]
	v_mfma_f32_16x16x32_f16 v[66:69], v[202:205], v[234:237], v[26:29]
	s_barrier
	s_setprio 0
	ds_read_b128 v[34:37], v215 offset:49152
	ds_read_b128 v[38:41], v215 offset:50176
	ds_read_b128 v[114:117], v215 offset:51200
	ds_read_b128 v[218:221], v215 offset:52224
	ds_read_b128 v[222:225], v215 offset:53248
	ds_read_b128 v[226:229], v215 offset:54272
	ds_read_b128 v[230:233], v215 offset:55296
	ds_read_b128 v[234:237], v215 offset:56320
	s_add_u32 m0, s35, 0x18000
	s_nop 0
	global_load_lds_dwordx4 v210, s[8:9]
	s_nop 0
	s_add_u32 m0, s35, 0x1a000
	s_nop 0
	global_load_lds_dwordx4 v212, s[8:9]
	s_add_u32 s8, s38, 0x40180
	s_addc_u32 s9, s39, 0
	s_add_u32 m0, s35, 0x1c000
	s_nop 0
	global_load_lds_dwordx4 v210, s[8:9]
	s_nop 0
	s_add_u32 m0, s35, 0x1e000
	s_nop 0
	global_load_lds_dwordx4 v212, s[8:9]
	s_nop 0
	s_add_u32 m0, s35, 0x8000
	s_nop 0
	global_load_lds_dwordx4 v1, s[6:7]
	s_nop 0
	s_add_u32 m0, s35, 0xa000
	s_nop 0
	global_load_lds_dwordx4 v211, s[6:7]
	s_waitcnt vmcnt(8)
	s_waitcnt lgkmcnt(0)
	s_barrier
	v_mfma_f32_16x16x32_f16 v[26:29], v[10:13], v[34:37], v[130:133]
	s_setprio 1
	v_mfma_f32_16x16x32_f16 v[62:65], v[14:17], v[38:41], v[26:29]
	v_mfma_f32_16x16x32_f16 v[26:29], v[22:25], v[38:41], v[146:149]
	v_mfma_f32_16x16x32_f16 v[58:61], v[18:21], v[34:37], v[26:29]
	v_mfma_f32_16x16x32_f16 v[26:29], v[10:13], v[114:117], v[150:153]
	v_mfma_f32_16x16x32_f16 v[46:49], v[14:17], v[218:221], v[26:29]
	v_mfma_f32_16x16x32_f16 v[26:29], v[22:25], v[218:221], v[154:157]
	v_mfma_f32_16x16x32_f16 v[42:45], v[18:21], v[114:117], v[26:29]
	v_mfma_f32_16x16x32_f16 v[26:29], v[10:13], v[222:225], v[158:161]
	v_mfma_f32_16x16x32_f16 v[30:33], v[14:17], v[226:229], v[26:29]
	v_mfma_f32_16x16x32_f16 v[26:29], v[22:25], v[226:229], v[162:165]
	v_mfma_f32_16x16x32_f16 v[26:29], v[18:21], v[222:225], v[26:29]
	v_mfma_f32_16x16x32_f16 v[2:5], v[10:13], v[230:233], v[2:5]
	v_mfma_f32_16x16x32_f16 v[14:17], v[14:17], v[234:237], v[2:5]
	v_mfma_f32_16x16x32_f16 v[2:5], v[22:25], v[234:237], v[6:9]
	v_mfma_f32_16x16x32_f16 v[10:13], v[18:21], v[230:233], v[2:5]
	v_mfma_f32_16x16x32_f16 v[2:5], v[190:193], v[34:37], v[166:169]
	v_mfma_f32_16x16x32_f16 v[54:57], v[194:197], v[38:41], v[2:5]
	v_mfma_f32_16x16x32_f16 v[2:5], v[202:205], v[38:41], v[170:173]
	v_mfma_f32_16x16x32_f16 v[50:53], v[198:201], v[34:37], v[2:5]
	v_mfma_f32_16x16x32_f16 v[2:5], v[190:193], v[114:117], v[174:177]
	v_mfma_f32_16x16x32_f16 v[38:41], v[194:197], v[218:221], v[2:5]
	v_mfma_f32_16x16x32_f16 v[2:5], v[202:205], v[218:221], v[178:181]
	v_mfma_f32_16x16x32_f16 v[34:37], v[198:201], v[114:117], v[2:5]
	v_mfma_f32_16x16x32_f16 v[2:5], v[190:193], v[222:225], v[182:185]
	v_mfma_f32_16x16x32_f16 v[22:25], v[194:197], v[226:229], v[2:5]
	v_mfma_f32_16x16x32_f16 v[2:5], v[202:205], v[226:229], v[118:121]
	v_mfma_f32_16x16x32_f16 v[18:21], v[198:201], v[222:225], v[2:5]
	v_mfma_f32_16x16x32_f16 v[2:5], v[190:193], v[230:233], v[186:189]
	v_mfma_f32_16x16x32_f16 v[6:9], v[194:197], v[234:237], v[2:5]
	v_mfma_f32_16x16x32_f16 v[2:5], v[202:205], v[234:237], v[122:125]
	v_mfma_f32_16x16x32_f16 v[2:5], v[198:201], v[230:233], v[2:5]
	s_barrier
	s_setprio 0
	s_mov_b32 s58, 0
	s_mov_b64 s[54:55], 0
	s_branch .LBB0_1165
